# added: epilogue trim (stale pads/waits removed, chained store addresses) in phases 6,8,12
# baseline (speedup 1.0000x reference)
; #define PG8_STAGE(bufoff, gbase, voff) do { _Pragma("unroll") for (int _i = 0; _i < 2; ++_i) \
;         __builtin_amdgcn_global_load_lds((const unsigned*)((const char*)(gbase) + (voff)[_i]), (LAS unsigned*)(lds + (bufoff) + ldsw + _i * 8192), 16, 0, 0); } while (0)
; #define PG8_LDA(dst, b, h) do { _Pragma("unroll") for (int m = 0; m < 4; ++m) _Pragma("unroll") for (int k = 0; k < 2; ++k) dst[m][k] = *(const LAS bf16x8*)(lds + PG8_SA(b, h) + aoff + m * 2048 + k * 1024); } while (0)
; #define PG8_LDB(dst, b, h) do { _Pragma("unroll") for (int n = 0; n < 2; ++n) _Pragma("unroll") for (int k = 0; k < 2; ++k) dst[n][k] = *(const LAS bf16x8*)(lds + PG8_SB(b, h) + boff + n * 2048 + k * 1024); } while (0)
; #define PG8_MMA(ai, bj, At, Bt) do { __builtin_amdgcn_s_setprio(1); _Pragma("unroll") for (int m = 0; m < 4; ++m) _Pragma("unroll") for (int n = 0; n < 2; ++n) _Pragma("unroll") for (int k = 0; k < 2; ++k) \
;         acc[ai][bj][m][n] = __builtin_amdgcn_mfma_f32_16x16x32_bf16(Bt[n][k], At[m][k], acc[ai][bj][m][n], 0, 0, 0); __builtin_amdgcn_s_setprio(0); } while (0)
; #define PG8_WAIT_L(n) asm volatile("s_waitcnt lgkmcnt(" #n ")" ::: "memory")
; #define PG8_BAR __builtin_amdgcn_s_barrier()
; #define PG8_SCHED __builtin_amdgcn_sched_barrier(0)
; template <class Epi>
; __device__ __forceinline__ void gemm_phase(LAS unsigned char* lds, const Gemm g, const StaticOrder& S, const Epi& E) {
;     ...
;         for (int t = 0; t < nt; t += 2) {
;             const bool last = (t == nt - 2);
;             const char* a1 = cA + (size_t)(t + 1) * kstep;
;             const char* a2 = last ? nA : cA + (size_t)(t + 2) * kstep; const char* b2 = last ? nB : cB + (size_t)(t + 2) * kstep;
;             const char* a3 = a2 + kstep; const char* b3 = b2 + kstep;
;             if (last) E.pre(cur, wr, fr, epre);
;             PG8_LDB(B0, 0, 0); PG8_SCHED; PG8_LDA(At, 0, 0); PG8_STAGE(PG8_SA(1, 1), a1 + hstepA, voffA);
;             PG8_WAIT_L(8); PG8_BAR; PG8_WAIT_L(0); PG8_MMA(0, 0, At, B0); PG8_BAR; PG8_SCHED;
;             PG8_LDB(B1, 0, 1); PG8_STAGE(PG8_SB(0, 0), b2, voffB);
;             PG8_BAR; PG8_WAIT_L(0); PG8_MMA(0, 1, At, B1); PG8_BAR;
;             PG8_LDA(At, 0, 1); PG8_STAGE(PG8_SA(0, 0), a2, voffA);
;             PG8_BAR; PG8_WAIT_L(0); PG8_MMA(1, 0, At, B0); PG8_BAR; PG8_SCHED;
.LBB0_770:
	ds_read_b128 v[146:149], v177
	ds_read_b128 v[154:157], v177 offset:1024
	ds_read_b128 v[158:161], v177 offset:2048
	ds_read_b128 v[162:165], v177 offset:3072
	s_add_u32 s22, s20, 0xfffc0080
	s_addc_u32 s23, s21, -1
	s_cmp_eq_u32 s45, 12
	s_cselect_b32 s25, s13, s23
	s_cselect_b32 s24, s41, s22
	s_cselect_b32 s23, s11, s44
	s_cselect_b32 s22, s42, s43
	v_lshl_add_u64 v[150:151], s[20:21], 0, v[138:139]
	s_add_i32 m0, s19, 0xc000
	ds_read_b128 v[166:169], v178
	ds_read_b128 v[170:173], v178 offset:1024
	ds_read_b128 v[182:185], v178 offset:2048
	ds_read_b128 v[186:189], v178 offset:3072
	ds_read_b128 v[190:193], v178 offset:4096
	ds_read_b128 v[194:197], v178 offset:5120
	ds_read_b128 v[198:201], v178 offset:6144
	ds_read_b128 v[202:205], v178 offset:7168
	global_load_lds_dwordx4 v[150:151], off
	v_lshl_add_u64 v[150:151], s[20:21], 0, v[140:141]
	s_add_i32 m0, s19, 0xe000
	s_nop 0
	global_load_lds_dwordx4 v[150:151], off
	s_waitcnt lgkmcnt(8)
	s_barrier
	s_waitcnt lgkmcnt(0)
	s_setprio 1
	s_waitcnt lgkmcnt(0)
	v_mfma_f32_16x16x32_bf16 v[124:127], v[146:149], v[166:169], v[124:127]
	v_mfma_f32_16x16x32_bf16 v[120:123], v[158:161], v[166:169], v[120:123]
	v_mfma_f32_16x16x32_bf16 v[108:111], v[146:149], v[182:185], v[108:111]
	v_mfma_f32_16x16x32_bf16 v[104:107], v[158:161], v[182:185], v[104:107]
	v_mfma_f32_16x16x32_bf16 v[92:95], v[146:149], v[190:193], v[92:95]
	v_mfma_f32_16x16x32_bf16 v[88:91], v[158:161], v[190:193], v[88:91]
	v_mfma_f32_16x16x32_bf16 v[76:79], v[146:149], v[198:201], v[76:79]
	v_mfma_f32_16x16x32_bf16 v[72:75], v[158:161], v[198:201], v[72:75]
	v_mfma_f32_16x16x32_bf16 v[124:127], v[154:157], v[170:173], v[124:127]
	v_mfma_f32_16x16x32_bf16 v[120:123], v[162:165], v[170:173], v[120:123]
	v_mfma_f32_16x16x32_bf16 v[108:111], v[154:157], v[186:189], v[108:111]
	v_mfma_f32_16x16x32_bf16 v[104:107], v[162:165], v[186:189], v[104:107]
	v_mfma_f32_16x16x32_bf16 v[92:95], v[154:157], v[194:197], v[92:95]
	v_mfma_f32_16x16x32_bf16 v[88:91], v[162:165], v[194:197], v[88:91]
	v_mfma_f32_16x16x32_bf16 v[76:79], v[154:157], v[202:205], v[76:79]
	v_mfma_f32_16x16x32_bf16 v[72:75], v[162:165], v[202:205], v[72:75]
	s_setprio 0
	s_barrier
	s_add_i32 s46, s7, s29
	v_lshl_add_u64 v[150:151], s[22:23], 0, v[130:131]
	s_mov_b32 m0, s46
	ds_read_b128 v[206:209], v179
	ds_read_b128 v[210:213], v179 offset:1024
	ds_read_b128 v[214:217], v179 offset:2048
	ds_read_b128 v[218:221], v179 offset:3072
	global_load_lds_dwordx4 v[150:151], off
	v_lshl_add_u64 v[222:223], s[22:23], 0, v[134:135]
	s_add_i32 m0, s46, 0x2000
	s_nop 0
	global_load_lds_dwordx4 v[222:223], off
	s_barrier
	s_waitcnt lgkmcnt(0)
	s_setprio 1
	s_waitcnt lgkmcnt(0)
	v_mfma_f32_16x16x32_bf16 v[116:119], v[206:209], v[166:169], v[116:119]
	v_mfma_f32_16x16x32_bf16 v[112:115], v[214:217], v[166:169], v[112:115]
	v_mfma_f32_16x16x32_bf16 v[100:103], v[206:209], v[182:185], v[100:103]
	v_mfma_f32_16x16x32_bf16 v[96:99], v[214:217], v[182:185], v[96:99]
	v_mfma_f32_16x16x32_bf16 v[84:87], v[206:209], v[190:193], v[84:87]
	v_mfma_f32_16x16x32_bf16 v[80:83], v[214:217], v[190:193], v[80:83]
	v_mfma_f32_16x16x32_bf16 v[68:71], v[206:209], v[198:201], v[68:71]
	v_mfma_f32_16x16x32_bf16 v[64:67], v[214:217], v[198:201], v[64:67]
	v_mfma_f32_16x16x32_bf16 v[116:119], v[210:213], v[170:173], v[116:119]
	v_mfma_f32_16x16x32_bf16 v[112:115], v[218:221], v[170:173], v[112:115]
	v_mfma_f32_16x16x32_bf16 v[100:103], v[210:213], v[186:189], v[100:103]
	v_mfma_f32_16x16x32_bf16 v[96:99], v[218:221], v[186:189], v[96:99]
	v_mfma_f32_16x16x32_bf16 v[84:87], v[210:213], v[194:197], v[84:87]
	v_mfma_f32_16x16x32_bf16 v[80:83], v[218:221], v[194:197], v[80:83]
	v_mfma_f32_16x16x32_bf16 v[68:71], v[210:213], v[202:205], v[68:71]
	v_mfma_f32_16x16x32_bf16 v[64:67], v[218:221], v[202:205], v[64:67]
	s_setprio 0
	s_mov_b32 m0, s19
	v_lshl_add_u64 v[224:225], s[24:25], 0, v[128:129]
	s_barrier
	ds_read_b128 v[166:169], v178 offset:16384
	ds_read_b128 v[170:173], v178 offset:17408
	ds_read_b128 v[182:185], v178 offset:18432
	ds_read_b128 v[186:189], v178 offset:19456
	ds_read_b128 v[190:193], v178 offset:20480
	ds_read_b128 v[194:197], v178 offset:21504
	ds_read_b128 v[198:201], v178 offset:22528
	ds_read_b128 v[202:205], v178 offset:23552
	global_load_lds_dwordx4 v[224:225], off
	v_lshl_add_u64 v[226:227], s[24:25], 0, v[132:133]
	s_mov_b32 m0, s30
	s_nop 0
	global_load_lds_dwordx4 v[226:227], off
	s_barrier
	s_waitcnt lgkmcnt(0)
	s_setprio 1
	s_waitcnt lgkmcnt(0)
	v_mfma_f32_16x16x32_bf16 v[60:63], v[146:149], v[166:169], v[60:63]
	v_mfma_f32_16x16x32_bf16 v[56:59], v[158:161], v[166:169], v[56:59]
	v_mfma_f32_16x16x32_bf16 v[44:47], v[146:149], v[182:185], v[44:47]
	v_mfma_f32_16x16x32_bf16 v[40:43], v[158:161], v[182:185], v[40:43]
	v_mfma_f32_16x16x32_bf16 v[28:31], v[146:149], v[190:193], v[28:31]
	v_mfma_f32_16x16x32_bf16 v[24:27], v[158:161], v[190:193], v[24:27]
	v_mfma_f32_16x16x32_bf16 v[12:15], v[146:149], v[198:201], v[12:15]
	v_mfma_f32_16x16x32_bf16 v[8:11], v[158:161], v[198:201], v[8:11]
	v_mfma_f32_16x16x32_bf16 v[60:63], v[154:157], v[170:173], v[60:63]
	v_mfma_f32_16x16x32_bf16 v[56:59], v[162:165], v[170:173], v[56:59]
	v_mfma_f32_16x16x32_bf16 v[44:47], v[154:157], v[186:189], v[44:47]
	v_mfma_f32_16x16x32_bf16 v[40:43], v[162:165], v[186:189], v[40:43]
	v_mfma_f32_16x16x32_bf16 v[28:31], v[154:157], v[194:197], v[28:31]
	v_mfma_f32_16x16x32_bf16 v[24:27], v[162:165], v[194:197], v[24:27]
	v_mfma_f32_16x16x32_bf16 v[12:15], v[154:157], v[202:205], v[12:15]
	v_mfma_f32_16x16x32_bf16 v[8:11], v[162:165], v[202:205], v[8:11]
	s_setprio 0
	s_barrier
; #define PG8_STAGE(bufoff, gbase, voff) do { _Pragma("unroll") for (int _i = 0; _i < 2; ++_i) \
;         __builtin_amdgcn_global_load_lds((const unsigned*)((const char*)(gbase) + (voff)[_i]), (LAS unsigned*)(lds + (bufoff) + ldsw + _i * 8192), 16, 0, 0); } while (0)
; #define PG8_LDA(dst, b, h) do { _Pragma("unroll") for (int m = 0; m < 4; ++m) _Pragma("unroll") for (int k = 0; k < 2; ++k) dst[m][k] = *(const LAS bf16x8*)(lds + PG8_SA(b, h) + aoff + m * 2048 + k * 1024); } while (0)
; #define PG8_LDB(dst, b, h) do { _Pragma("unroll") for (int n = 0; n < 2; ++n) _Pragma("unroll") for (int k = 0; k < 2; ++k) dst[n][k] = *(const LAS bf16x8*)(lds + PG8_SB(b, h) + boff + n * 2048 + k * 1024); } while (0)
; #define PG8_MMA(ai, bj, At, Bt) do { __builtin_amdgcn_s_setprio(1); _Pragma("unroll") for (int m = 0; m < 4; ++m) _Pragma("unroll") for (int n = 0; n < 2; ++n) _Pragma("unroll") for (int k = 0; k < 2; ++k) \
;         acc[ai][bj][m][n] = __builtin_amdgcn_mfma_f32_16x16x32_bf16(Bt[n][k], At[m][k], acc[ai][bj][m][n], 0, 0, 0); __builtin_amdgcn_s_setprio(0); } while (0)
; #define PG8_WAIT_V(n) asm volatile("s_waitcnt vmcnt(" #n ")" ::: "memory")
; #define PG8_WAIT_L(n) asm volatile("s_waitcnt lgkmcnt(" #n ")" ::: "memory")
; #define PG8_BAR __builtin_amdgcn_s_barrier()
; #define PG8_SCHED __builtin_amdgcn_sched_barrier(0)
; template <class Epi>
; __device__ __forceinline__ void gemm_phase(LAS unsigned char* lds, const Gemm g, const StaticOrder& S, const Epi& E) {
;     ...
;             PG8_STAGE(PG8_SB(0, 1), b2 + hstepB, voffB);
;             PG8_WAIT_V(6); PG8_BAR; PG8_MMA(1, 1, At, B1); PG8_BAR;
;             PG8_LDB(B0, 1, 0); PG8_SCHED; PG8_LDA(At, 1, 0); PG8_STAGE(PG8_SA(0, 1), a2 + hstepA, voffA);
;             PG8_WAIT_L(8); PG8_BAR; PG8_WAIT_L(0); PG8_MMA(0, 0, At, B0); PG8_BAR; PG8_SCHED;
;             PG8_LDB(B1, 1, 1); PG8_STAGE(PG8_SB(1, 0), b3, voffB);
;             PG8_BAR; PG8_WAIT_L(0); PG8_MMA(0, 1, At, B1); PG8_BAR;
;             PG8_LDA(At, 1, 1); PG8_STAGE(PG8_SA(1, 0), a3, voffA);
;             PG8_BAR; PG8_WAIT_L(0); PG8_MMA(1, 0, At, B0); PG8_BAR; PG8_SCHED;
	s_add_u32 s46, s22, 0x40000
	s_addc_u32 s47, s23, 0
	s_add_i32 s48, s38, s29
	v_lshl_add_u64 v[146:147], s[46:47], 0, v[130:131]
	s_mov_b32 m0, s48
	s_nop 0
	global_load_lds_dwordx4 v[146:147], off
	v_lshl_add_u64 v[146:147], s[46:47], 0, v[134:135]
	s_add_i32 m0, s48, 0x2000
	s_nop 0
	global_load_lds_dwordx4 v[146:147], off
	s_waitcnt vmcnt(6)
	s_barrier
	s_setprio 1
	v_mfma_f32_16x16x32_bf16 v[52:55], v[206:209], v[166:169], v[52:55]
	v_mfma_f32_16x16x32_bf16 v[48:51], v[214:217], v[166:169], v[48:51]
	v_mfma_f32_16x16x32_bf16 v[36:39], v[206:209], v[182:185], v[36:39]
	v_mfma_f32_16x16x32_bf16 v[32:35], v[214:217], v[182:185], v[32:35]
	v_mfma_f32_16x16x32_bf16 v[20:23], v[206:209], v[190:193], v[20:23]
	v_mfma_f32_16x16x32_bf16 v[16:19], v[214:217], v[190:193], v[16:19]
	v_mfma_f32_16x16x32_bf16 v[4:7], v[206:209], v[198:201], v[4:7]
	v_mfma_f32_16x16x32_bf16 v[0:3], v[214:217], v[198:201], v[0:3]
	v_mfma_f32_16x16x32_bf16 v[52:55], v[210:213], v[170:173], v[52:55]
	v_mfma_f32_16x16x32_bf16 v[48:51], v[218:221], v[170:173], v[48:51]
	v_mfma_f32_16x16x32_bf16 v[36:39], v[210:213], v[186:189], v[36:39]
	v_mfma_f32_16x16x32_bf16 v[32:35], v[218:221], v[186:189], v[32:35]
	v_mfma_f32_16x16x32_bf16 v[20:23], v[210:213], v[194:197], v[20:23]
	v_mfma_f32_16x16x32_bf16 v[16:19], v[218:221], v[194:197], v[16:19]
	v_mfma_f32_16x16x32_bf16 v[4:7], v[210:213], v[202:205], v[4:7]
	v_mfma_f32_16x16x32_bf16 v[0:3], v[218:221], v[202:205], v[0:3]
	s_setprio 0
	s_add_i32 s46, 0, 0x18000
	v_add_u32_e32 v162, s46, v175
	s_barrier
	ds_read_b128 v[146:149], v162
	ds_read_b128 v[154:157], v162 offset:1024
	ds_read_b128 v[158:161], v162 offset:2048
	ds_read_b128 v[162:165], v162 offset:3072
	s_add_u32 s24, s24, 0x40000
	s_addc_u32 s25, s25, 0
	s_mov_b32 m0, s31
	v_lshl_add_u64 v[206:207], s[24:25], 0, v[128:129]
	ds_read_b128 v[166:169], v178 offset:32768
	ds_read_b128 v[170:173], v178 offset:33792
	ds_read_b128 v[182:185], v178 offset:34816
	ds_read_b128 v[186:189], v178 offset:35840
	ds_read_b128 v[190:193], v178 offset:36864
	ds_read_b128 v[194:197], v178 offset:37888
	ds_read_b128 v[198:201], v178 offset:38912
	ds_read_b128 v[202:205], v178 offset:39936
	global_load_lds_dwordx4 v[206:207], off
	v_lshl_add_u64 v[206:207], s[24:25], 0, v[132:133]
	s_mov_b32 m0, s33
	s_nop 0
	global_load_lds_dwordx4 v[206:207], off
	s_waitcnt lgkmcnt(8)
	s_barrier
	s_waitcnt lgkmcnt(0)
	s_setprio 1
	s_waitcnt lgkmcnt(0)
	v_mfma_f32_16x16x32_bf16 v[124:127], v[146:149], v[166:169], v[124:127]
	v_mfma_f32_16x16x32_bf16 v[120:123], v[158:161], v[166:169], v[120:123]
	v_mfma_f32_16x16x32_bf16 v[108:111], v[146:149], v[182:185], v[108:111]
	v_mfma_f32_16x16x32_bf16 v[104:107], v[158:161], v[182:185], v[104:107]
	v_mfma_f32_16x16x32_bf16 v[92:95], v[146:149], v[190:193], v[92:95]
	v_mfma_f32_16x16x32_bf16 v[88:91], v[158:161], v[190:193], v[88:91]
	v_mfma_f32_16x16x32_bf16 v[76:79], v[146:149], v[198:201], v[76:79]
	v_mfma_f32_16x16x32_bf16 v[72:75], v[158:161], v[198:201], v[72:75]
	v_mfma_f32_16x16x32_bf16 v[124:127], v[154:157], v[170:173], v[124:127]
	v_mfma_f32_16x16x32_bf16 v[120:123], v[162:165], v[170:173], v[120:123]
	v_mfma_f32_16x16x32_bf16 v[108:111], v[154:157], v[186:189], v[108:111]
	v_mfma_f32_16x16x32_bf16 v[104:107], v[162:165], v[186:189], v[104:107]
	v_mfma_f32_16x16x32_bf16 v[92:95], v[154:157], v[194:197], v[92:95]
	v_mfma_f32_16x16x32_bf16 v[88:91], v[162:165], v[194:197], v[88:91]
	v_mfma_f32_16x16x32_bf16 v[76:79], v[154:157], v[202:205], v[76:79]
	v_mfma_f32_16x16x32_bf16 v[72:75], v[162:165], v[202:205], v[72:75]
	s_setprio 0
	s_barrier
	s_add_i32 s24, 0, 0x1c000
	s_add_i32 s25, s46, s29
	v_add_u32_e32 v181, s24, v175
	v_lshl_add_u64 v[150:151], v[150:151], 0, s[4:5]
	s_mov_b32 m0, s25
	ds_read_b128 v[206:209], v181
	ds_read_b128 v[210:213], v181 offset:1024
	ds_read_b128 v[214:217], v181 offset:2048
	ds_read_b128 v[218:221], v181 offset:3072
	global_load_lds_dwordx4 v[150:151], off
	v_lshl_add_u64 v[150:151], v[222:223], 0, s[4:5]
	s_add_i32 m0, s25, 0x2000
	s_nop 0
	global_load_lds_dwordx4 v[150:151], off
	s_barrier
	s_waitcnt lgkmcnt(0)
	s_setprio 1
	s_waitcnt lgkmcnt(0)
	v_mfma_f32_16x16x32_bf16 v[116:119], v[206:209], v[166:169], v[116:119]
	v_mfma_f32_16x16x32_bf16 v[112:115], v[214:217], v[166:169], v[112:115]
	v_mfma_f32_16x16x32_bf16 v[100:103], v[206:209], v[182:185], v[100:103]
	v_mfma_f32_16x16x32_bf16 v[96:99], v[214:217], v[182:185], v[96:99]
	v_mfma_f32_16x16x32_bf16 v[84:87], v[206:209], v[190:193], v[84:87]
	v_mfma_f32_16x16x32_bf16 v[80:83], v[214:217], v[190:193], v[80:83]
	v_mfma_f32_16x16x32_bf16 v[68:71], v[206:209], v[198:201], v[68:71]
	v_mfma_f32_16x16x32_bf16 v[64:67], v[214:217], v[198:201], v[64:67]
	v_mfma_f32_16x16x32_bf16 v[116:119], v[210:213], v[170:173], v[116:119]
	v_mfma_f32_16x16x32_bf16 v[112:115], v[218:221], v[170:173], v[112:115]
	v_mfma_f32_16x16x32_bf16 v[100:103], v[210:213], v[186:189], v[100:103]
	v_mfma_f32_16x16x32_bf16 v[96:99], v[218:221], v[186:189], v[96:99]
	v_mfma_f32_16x16x32_bf16 v[84:87], v[210:213], v[194:197], v[84:87]
	v_mfma_f32_16x16x32_bf16 v[80:83], v[218:221], v[194:197], v[80:83]
	v_mfma_f32_16x16x32_bf16 v[68:71], v[210:213], v[202:205], v[68:71]
	v_mfma_f32_16x16x32_bf16 v[64:67], v[218:221], v[202:205], v[64:67]
	s_setprio 0
	s_mov_b32 m0, s35
	v_lshl_add_u64 v[150:151], v[224:225], 0, s[4:5]
	s_barrier
	ds_read_b128 v[166:169], v178 offset:49152
	ds_read_b128 v[170:173], v178 offset:50176
	ds_read_b128 v[182:185], v178 offset:51200
	ds_read_b128 v[186:189], v178 offset:52224
	ds_read_b128 v[190:193], v178 offset:53248
	ds_read_b128 v[194:197], v178 offset:54272
	ds_read_b128 v[198:201], v178 offset:55296
	ds_read_b128 v[202:205], v178 offset:56320
	global_load_lds_dwordx4 v[150:151], off
	v_lshl_add_u64 v[150:151], v[226:227], 0, s[4:5]
	s_mov_b32 m0, s36
	s_nop 0
	global_load_lds_dwordx4 v[150:151], off
	s_barrier
; __device__ __forceinline__ unsigned pk2(float lo, float hi) { const f32x2 v = (f32x2){lo, hi}; const bf16x2_t b = __builtin_convertvector(v, bf16x2_t); return __builtin_bit_cast(unsigned, b); }
; #define PG8_STAGE(bufoff, gbase, voff) do { _Pragma("unroll") for (int _i = 0; _i < 2; ++_i) \
;         __builtin_amdgcn_global_load_lds((const unsigned*)((const char*)(gbase) + (voff)[_i]), (LAS unsigned*)(lds + (bufoff) + ldsw + _i * 8192), 16, 0, 0); } while (0)
; #define PG8_LDA(dst, b, h) do { _Pragma("unroll") for (int m = 0; m < 4; ++m) _Pragma("unroll") for (int k = 0; k < 2; ++k) dst[m][k] = *(const LAS bf16x8*)(lds + PG8_SA(b, h) + aoff + m * 2048 + k * 1024); } while (0)
; #define PG8_WAIT_V(n) asm volatile("s_waitcnt vmcnt(" #n ")" ::: "memory")
; #define PG8_BAR __builtin_amdgcn_s_barrier()
;     __device__ __forceinline__ void operator()(const f32x4 (&acc)[2][2][4][2], const Unit& u, int wr, int wc, int fr, int fq, const float (&)[8]) const {
;     ...
;         const int col0 = u.pn * BM + wc * 32 + 8 * fq;
; #pragma unroll
;         for (int ai = 0; ai < 2; ++ai)
; #pragma unroll
;             for (int m = 0; m < 4; ++m) { const int row = row0 + ai * HALF + m * 16; const float rs = rsqrtf(ep[ai * 4 + m] * (1.0f / 1024.0f) + EPS);
;                 u16* rowp = O + (size_t)row * ldc + col0;
; #pragma unroll
;                 for (int bj = 0; bj < 2; ++bj) { f32x4 v0 = acc[ai][bj][m][0] * rs, v1 = acc[ai][bj][m][1] * rs;
;                     if (ACT == 1) {
; #pragma unroll
;                         for (int j = 0; j < 4; ++j) { const float a0 = fmaxf(v0[j], 0.f), a1 = fmaxf(v1[j], 0.f); v0[j] = a0 * a0; v1[j] = a1 * a1; } }
;                     u32x4 w; w.x = pk2(v0[0], v0[1]); w.y = pk2(v0[2], v0[3]); w.z = pk2(v1[0], v1[1]); w.w = pk2(v1[2], v1[3]);
;                     *(u32x4*)(rowp + bj * HALF) = w; } }
; template <class Epi>
; __device__ __forceinline__ void gemm_phase(LAS unsigned char* lds, const Gemm g, const StaticOrder& S, const Epi& E) {
;     ...
;             PG8_BAR; PG8_WAIT_L(0); PG8_MMA(0, 1, At, B1); PG8_BAR;
;             PG8_LDA(At, 1, 1); PG8_STAGE(PG8_SA(1, 0), a3, voffA);
;             PG8_BAR; PG8_WAIT_L(0); PG8_MMA(1, 0, At, B0); PG8_BAR; PG8_SCHED;
;             PG8_STAGE(PG8_SB(1, 1), b3 + hstepB, voffB);
;             PG8_WAIT_V(6); PG8_BAR; PG8_MMA(1, 1, At, B1); PG8_BAR;
;         }
;         E(acc, cur, wr, wc, fr, fq, epre);
	s_waitcnt lgkmcnt(0)
	s_setprio 1
	s_waitcnt lgkmcnt(0)
	v_mfma_f32_16x16x32_bf16 v[60:63], v[146:149], v[166:169], v[60:63]
	v_mfma_f32_16x16x32_bf16 v[56:59], v[158:161], v[166:169], v[56:59]
	v_mfma_f32_16x16x32_bf16 v[44:47], v[146:149], v[182:185], v[44:47]
	v_mfma_f32_16x16x32_bf16 v[40:43], v[158:161], v[182:185], v[40:43]
	v_mfma_f32_16x16x32_bf16 v[28:31], v[146:149], v[190:193], v[28:31]
	v_mfma_f32_16x16x32_bf16 v[24:27], v[158:161], v[190:193], v[24:27]
	v_mfma_f32_16x16x32_bf16 v[12:15], v[146:149], v[198:201], v[12:15]
	v_mfma_f32_16x16x32_bf16 v[8:11], v[158:161], v[198:201], v[8:11]
	v_mfma_f32_16x16x32_bf16 v[60:63], v[154:157], v[170:173], v[60:63]
	v_mfma_f32_16x16x32_bf16 v[56:59], v[162:165], v[170:173], v[56:59]
	v_mfma_f32_16x16x32_bf16 v[44:47], v[154:157], v[186:189], v[44:47]
	v_mfma_f32_16x16x32_bf16 v[40:43], v[162:165], v[186:189], v[40:43]
	v_mfma_f32_16x16x32_bf16 v[28:31], v[154:157], v[194:197], v[28:31]
	v_mfma_f32_16x16x32_bf16 v[24:27], v[162:165], v[194:197], v[24:27]
	v_mfma_f32_16x16x32_bf16 v[12:15], v[154:157], v[202:205], v[12:15]
	v_mfma_f32_16x16x32_bf16 v[8:11], v[162:165], v[202:205], v[8:11]
	s_setprio 0
	s_barrier
	s_add_u32 s22, s22, 0x40080
	s_addc_u32 s23, s23, 0
	s_add_i32 s24, s24, s29
	v_lshl_add_u64 v[146:147], s[22:23], 0, v[130:131]
	s_mov_b32 m0, s24
	s_nop 0
	global_load_lds_dwordx4 v[146:147], off
	v_lshl_add_u64 v[146:147], s[22:23], 0, v[134:135]
	s_add_i32 m0, s24, 0x2000
	s_nop 0
	global_load_lds_dwordx4 v[146:147], off
	s_waitcnt vmcnt(6)
	s_barrier
	s_setprio 1
	v_mfma_f32_16x16x32_bf16 v[52:55], v[206:209], v[166:169], v[52:55]
	v_mfma_f32_16x16x32_bf16 v[48:51], v[214:217], v[166:169], v[48:51]
	v_mfma_f32_16x16x32_bf16 v[36:39], v[206:209], v[182:185], v[36:39]
	v_mfma_f32_16x16x32_bf16 v[32:35], v[214:217], v[182:185], v[32:35]
	v_mfma_f32_16x16x32_bf16 v[20:23], v[206:209], v[190:193], v[20:23]
	v_mfma_f32_16x16x32_bf16 v[16:19], v[214:217], v[190:193], v[16:19]
	v_mfma_f32_16x16x32_bf16 v[4:7], v[206:209], v[198:201], v[4:7]
	v_mfma_f32_16x16x32_bf16 v[0:3], v[214:217], v[198:201], v[0:3]
	v_mfma_f32_16x16x32_bf16 v[52:55], v[210:213], v[170:173], v[52:55]
	v_mfma_f32_16x16x32_bf16 v[48:51], v[218:221], v[170:173], v[48:51]
	v_mfma_f32_16x16x32_bf16 v[36:39], v[210:213], v[186:189], v[36:39]
	v_mfma_f32_16x16x32_bf16 v[32:35], v[218:221], v[186:189], v[32:35]
	v_mfma_f32_16x16x32_bf16 v[20:23], v[210:213], v[194:197], v[20:23]
	v_mfma_f32_16x16x32_bf16 v[16:19], v[218:221], v[194:197], v[16:19]
	v_mfma_f32_16x16x32_bf16 v[4:7], v[210:213], v[202:205], v[4:7]
	v_mfma_f32_16x16x32_bf16 v[0:3], v[218:221], v[202:205], v[0:3]
	s_setprio 0
	s_add_i32 s45, s45, 2
	s_add_u32 s20, s20, 0x100
	s_addc_u32 s21, s21, 0
	s_add_u32 s43, s43, 0x100
	s_addc_u32 s44, s44, 0
	s_cmp_gt_u32 s45, 13
	s_barrier
	s_cbranch_scc0 .LBB0_770
	s_mov_b64 s[24:25], 0x20000
	s_mov_b64 s[42:43], 0xa0000
	s_bfe_u32 vcc_lo, s18, 0x20003
	s_lshl_b32 vcc_lo, vcc_lo, 10
	s_add_i32 vcc_lo, vcc_lo, 0x20010
	v_lshl_add_u32 v236, v174, 2, vcc_lo
	ds_read_b32 v228, v236
	ds_read_b32 v229, v236 offset:64
	ds_read_b32 v230, v236 offset:128
	ds_read_b32 v231, v236 offset:192
	ds_read_b32 v232, v236 offset:512
	ds_read_b32 v233, v236 offset:576
	ds_read_b32 v234, v236 offset:640
	ds_read_b32 v235, v236 offset:704
	s_waitcnt lgkmcnt(0)
	v_lshl_add_u32 v148, s18, 8, v174
	v_ashrrev_i32_e32 v149, 31, v148
	v_lshl_or_b32 v166, s40, 8, v176
	v_ashrrev_i32_e32 v167, 31, v166
	v_lshlrev_b64 v[170:171], 13, v[148:149]
	v_lshlrev_b64 v[148:149], 1, v[166:167]
	v_lshl_add_u64 v[166:167], s[96:97], 0, v[170:171]
	v_lshl_add_u64 v[212:213], v[166:167], 0, v[148:149]
	s_mov_b32 s40, s10
	s_mov_b32 s18, s12
	s_mov_b64 s[22:23], s[16:17]
	s_mov_b64 s[20:21], s[14:15]
	v_mov_b32_e32 v184, v228
	v_pk_mul_f32 v[120:121], v[120:121], v[184:185] op_sel_hi:[1,0]
	v_pk_mul_f32 v[126:127], v[126:127], v[184:185] op_sel_hi:[1,0]
	v_pk_mul_f32 v[124:125], v[124:125], v[184:185] op_sel_hi:[1,0]
	v_pk_mul_f32 v[122:123], v[122:123], v[184:185] op_sel_hi:[1,0]
	v_max_f32_e32 v120, 0, v120
	v_max_f32_e32 v121, 0, v121
	v_max_f32_e32 v124, 0, v124
	v_max_f32_e32 v125, 0, v125
	v_pk_mul_f32 v[190:191], v[120:121], v[120:121]
	v_max_f32_e32 v120, 0, v126
	v_max_f32_e32 v122, 0, v122
	v_max_f32_e32 v121, 0, v127
	v_max_f32_e32 v123, 0, v123
	v_pk_mul_f32 v[124:125], v[124:125], v[124:125]
	v_pk_mul_f32 v[126:127], v[120:121], v[120:121]
	v_pk_mul_f32 v[194:195], v[122:123], v[122:123]
	v_pk_mul_f32 v[114:115], v[114:115], v[184:185] op_sel_hi:[1,0]
	v_cvt_pk_bf16_f32 v120, v124, v125
	v_cvt_pk_bf16_f32 v121, v126, v127
	v_cvt_pk_bf16_f32 v122, v190, v191
	v_cvt_pk_bf16_f32 v123, v194, v195
	v_pk_mul_f32 v[116:117], v[116:117], v[184:185] op_sel_hi:[1,0]
	v_pk_mul_f32 v[112:113], v[112:113], v[184:185] op_sel_hi:[1,0]
	v_max_f32_e32 v114, 0, v114
	v_max_f32_e32 v115, 0, v115
	global_store_dwordx4 v[212:213], v[120:123], off
	v_pk_mul_f32 v[118:119], v[118:119], v[184:185] op_sel_hi:[1,0]
	v_max_f32_e32 v116, 0, v116
	v_max_f32_e32 v112, 0, v112
	v_max_f32_e32 v117, 0, v117
	v_max_f32_e32 v113, 0, v113
	v_pk_mul_f32 v[122:123], v[114:115], v[114:115]
	v_pk_mul_f32 v[116:117], v[116:117], v[116:117]
	v_pk_mul_f32 v[120:121], v[112:113], v[112:113]
	v_max_f32_e32 v112, 0, v118
	v_max_f32_e32 v113, 0, v119
	v_pk_mul_f32 v[118:119], v[112:113], v[112:113]
	v_cvt_pk_bf16_f32 v112, v116, v117
	v_cvt_pk_bf16_f32 v113, v118, v119
	v_cvt_pk_bf16_f32 v114, v120, v121
	v_cvt_pk_bf16_f32 v115, v122, v123
	global_store_dwordx4 v[212:213], v[112:115], off offset:256
	s_nop 1
	v_mov_b32_e32 v112, v229
	v_pk_mul_f32 v[104:105], v[104:105], v[112:113] op_sel_hi:[1,0]
; __device__ __forceinline__ unsigned pk2(float lo, float hi) { const f32x2 v = (f32x2){lo, hi}; const bf16x2_t b = __builtin_convertvector(v, bf16x2_t); return __builtin_bit_cast(unsigned, b); }
;     __device__ __forceinline__ void operator()(const f32x4 (&acc)[2][2][4][2], const Unit& u, int wr, int wc, int fr, int fq, const float (&)[8]) const {
;     ...
;         for (int ai = 0; ai < 2; ++ai)
; #pragma unroll
;             for (int m = 0; m < 4; ++m) { const int row = row0 + ai * HALF + m * 16; const float rs = rsqrtf(ep[ai * 4 + m] * (1.0f / 1024.0f) + EPS);
;                 u16* rowp = O + (size_t)row * ldc + col0;
; #pragma unroll
;                 for (int bj = 0; bj < 2; ++bj) { f32x4 v0 = acc[ai][bj][m][0] * rs, v1 = acc[ai][bj][m][1] * rs;
;                     if (ACT == 1) {
; #pragma unroll
;                         for (int j = 0; j < 4; ++j) { const float a0 = fmaxf(v0[j], 0.f), a1 = fmaxf(v1[j], 0.f); v0[j] = a0 * a0; v1[j] = a1 * a1; } }
;                     u32x4 w; w.x = pk2(v0[0], v0[1]); w.y = pk2(v0[2], v0[3]); w.z = pk2(v1[0], v1[1]); w.w = pk2(v1[2], v1[3]);
;                     *(u32x4*)(rowp + bj * HALF) = w; } }
	v_pk_mul_f32 v[110:111], v[110:111], v[112:113] op_sel_hi:[1,0]
	v_pk_mul_f32 v[108:109], v[108:109], v[112:113] op_sel_hi:[1,0]
	v_pk_mul_f32 v[106:107], v[106:107], v[112:113] op_sel_hi:[1,0]
	v_max_f32_e32 v104, 0, v104
	v_max_f32_e32 v105, 0, v105
	v_max_f32_e32 v108, 0, v108
	v_max_f32_e32 v109, 0, v109
	v_pk_mul_f32 v[116:117], v[104:105], v[104:105]
	v_max_f32_e32 v104, 0, v110
	v_max_f32_e32 v106, 0, v106
	v_max_f32_e32 v105, 0, v111
	v_max_f32_e32 v107, 0, v107
	v_pk_mul_f32 v[108:109], v[108:109], v[108:109]
	v_pk_mul_f32 v[110:111], v[104:105], v[104:105]
	v_pk_mul_f32 v[118:119], v[106:107], v[106:107]
	v_pk_mul_f32 v[96:97], v[96:97], v[112:113] op_sel_hi:[1,0]
	v_lshl_add_u64 v[114:115], v[212:213], 0, s[24:25]
	v_cvt_pk_bf16_f32 v104, v108, v109
	v_cvt_pk_bf16_f32 v105, v110, v111
	v_cvt_pk_bf16_f32 v106, v116, v117
	v_cvt_pk_bf16_f32 v107, v118, v119
	v_pk_mul_f32 v[102:103], v[102:103], v[112:113] op_sel_hi:[1,0]
	v_max_f32_e32 v96, 0, v96
	v_max_f32_e32 v97, 0, v97
	global_store_dwordx4 v[114:115], v[104:107], off
	v_pk_mul_f32 v[100:101], v[100:101], v[112:113] op_sel_hi:[1,0]
	v_pk_mul_f32 v[98:99], v[98:99], v[112:113] op_sel_hi:[1,0]
	v_pk_mul_f32 v[104:105], v[96:97], v[96:97]
	v_max_f32_e32 v96, 0, v102
	v_max_f32_e32 v97, 0, v103
	v_max_f32_e32 v100, 0, v100
	v_max_f32_e32 v101, 0, v101
	v_pk_mul_f32 v[100:101], v[100:101], v[100:101]
	v_pk_mul_f32 v[108:109], v[96:97], v[96:97]
	v_cvt_pk_bf16_f32 v96, v100, v101
	v_max_f32_e32 v98, 0, v98
	v_max_f32_e32 v99, 0, v99
	v_pk_mul_f32 v[110:111], v[98:99], v[98:99]
	v_cvt_pk_bf16_f32 v97, v108, v109
	v_cvt_pk_bf16_f32 v98, v104, v105
	v_cvt_pk_bf16_f32 v99, v110, v111
	global_store_dwordx4 v[114:115], v[96:99], off offset:256
	s_nop 1
	v_lshl_add_u64 v[98:99], v[114:115], 0, s[24:25]
	v_mov_b32_e32 v100, v230
	v_pk_mul_f32 v[88:89], v[88:89], v[100:101] op_sel_hi:[1,0]
	v_pk_mul_f32 v[94:95], v[94:95], v[100:101] op_sel_hi:[1,0]
	v_pk_mul_f32 v[92:93], v[92:93], v[100:101] op_sel_hi:[1,0]
	v_pk_mul_f32 v[90:91], v[90:91], v[100:101] op_sel_hi:[1,0]
	v_max_f32_e32 v88, 0, v88
	v_max_f32_e32 v89, 0, v89
	v_max_f32_e32 v92, 0, v92
	v_max_f32_e32 v93, 0, v93
	v_pk_mul_f32 v[102:103], v[88:89], v[88:89]
	v_max_f32_e32 v88, 0, v94
	v_max_f32_e32 v90, 0, v90
	v_max_f32_e32 v89, 0, v95
	v_max_f32_e32 v91, 0, v91
	v_pk_mul_f32 v[92:93], v[92:93], v[92:93]
	v_pk_mul_f32 v[94:95], v[88:89], v[88:89]
	v_pk_mul_f32 v[104:105], v[90:91], v[90:91]
	v_pk_mul_f32 v[82:83], v[82:83], v[100:101] op_sel_hi:[1,0]
	v_cvt_pk_bf16_f32 v88, v92, v93
	v_cvt_pk_bf16_f32 v89, v94, v95
	v_cvt_pk_bf16_f32 v90, v102, v103
	v_cvt_pk_bf16_f32 v91, v104, v105
	v_pk_mul_f32 v[84:85], v[84:85], v[100:101] op_sel_hi:[1,0]
	v_pk_mul_f32 v[80:81], v[80:81], v[100:101] op_sel_hi:[1,0]
	v_max_f32_e32 v82, 0, v82
	v_max_f32_e32 v83, 0, v83
	global_store_dwordx4 v[98:99], v[88:91], off
	v_pk_mul_f32 v[86:87], v[86:87], v[100:101] op_sel_hi:[1,0]
	v_max_f32_e32 v84, 0, v84
	v_max_f32_e32 v80, 0, v80
	v_max_f32_e32 v85, 0, v85
	v_max_f32_e32 v81, 0, v81
	v_pk_mul_f32 v[90:91], v[82:83], v[82:83]
	v_pk_mul_f32 v[84:85], v[84:85], v[84:85]
	v_pk_mul_f32 v[88:89], v[80:81], v[80:81]
	v_max_f32_e32 v80, 0, v86
	v_max_f32_e32 v81, 0, v87
	v_pk_mul_f32 v[86:87], v[80:81], v[80:81]
	v_cvt_pk_bf16_f32 v80, v84, v85
	v_cvt_pk_bf16_f32 v81, v86, v87
	v_cvt_pk_bf16_f32 v82, v88, v89
	v_cvt_pk_bf16_f32 v83, v90, v91
	global_store_dwordx4 v[98:99], v[80:83], off offset:256
	s_nop 1
	v_mov_b32_e32 v80, v231
	v_pk_mul_f32 v[72:73], v[72:73], v[80:81] op_sel_hi:[1,0]
	v_pk_mul_f32 v[78:79], v[78:79], v[80:81] op_sel_hi:[1,0]
	v_pk_mul_f32 v[76:77], v[76:77], v[80:81] op_sel_hi:[1,0]
	v_pk_mul_f32 v[74:75], v[74:75], v[80:81] op_sel_hi:[1,0]
	v_max_f32_e32 v72, 0, v72
	v_max_f32_e32 v73, 0, v73
	v_max_f32_e32 v76, 0, v76
	v_max_f32_e32 v77, 0, v77
	v_pk_mul_f32 v[84:85], v[72:73], v[72:73]
	v_max_f32_e32 v72, 0, v78
	v_max_f32_e32 v74, 0, v74
	v_max_f32_e32 v73, 0, v79
	v_max_f32_e32 v75, 0, v75
	v_pk_mul_f32 v[76:77], v[76:77], v[76:77]
	v_pk_mul_f32 v[78:79], v[72:73], v[72:73]
	v_pk_mul_f32 v[86:87], v[74:75], v[74:75]
	v_pk_mul_f32 v[64:65], v[64:65], v[80:81] op_sel_hi:[1,0]
	v_lshl_add_u64 v[82:83], v[98:99], 0, s[24:25]
	v_cvt_pk_bf16_f32 v72, v76, v77
	v_cvt_pk_bf16_f32 v73, v78, v79
	v_cvt_pk_bf16_f32 v74, v84, v85
	v_cvt_pk_bf16_f32 v75, v86, v87
	v_pk_mul_f32 v[70:71], v[70:71], v[80:81] op_sel_hi:[1,0]
	v_max_f32_e32 v64, 0, v64
	v_max_f32_e32 v65, 0, v65
	global_store_dwordx4 v[82:83], v[72:75], off
	v_pk_mul_f32 v[68:69], v[68:69], v[80:81] op_sel_hi:[1,0]
	v_pk_mul_f32 v[66:67], v[66:67], v[80:81] op_sel_hi:[1,0]
	v_pk_mul_f32 v[72:73], v[64:65], v[64:65]
	v_max_f32_e32 v64, 0, v70
	v_max_f32_e32 v65, 0, v71
	v_max_f32_e32 v68, 0, v68
	v_max_f32_e32 v69, 0, v69
	v_pk_mul_f32 v[68:69], v[68:69], v[68:69]
	v_pk_mul_f32 v[76:77], v[64:65], v[64:65]
	v_cvt_pk_bf16_f32 v64, v68, v69
	v_max_f32_e32 v66, 0, v66
	v_max_f32_e32 v67, 0, v67
	v_pk_mul_f32 v[78:79], v[66:67], v[66:67]
	v_cvt_pk_bf16_f32 v65, v76, v77
	v_cvt_pk_bf16_f32 v66, v72, v73
	v_cvt_pk_bf16_f32 v67, v78, v79
	global_store_dwordx4 v[82:83], v[64:67], off offset:256
	s_nop 1
	v_lshl_add_u64 v[66:67], v[82:83], 0, s[42:43]
	v_mov_b32_e32 v68, v232
	v_pk_mul_f32 v[56:57], v[56:57], v[68:69] op_sel_hi:[1,0]
	v_pk_mul_f32 v[62:63], v[62:63], v[68:69] op_sel_hi:[1,0]
	v_pk_mul_f32 v[60:61], v[60:61], v[68:69] op_sel_hi:[1,0]
	v_pk_mul_f32 v[58:59], v[58:59], v[68:69] op_sel_hi:[1,0]
	v_max_f32_e32 v56, 0, v56
	v_max_f32_e32 v57, 0, v57
	v_max_f32_e32 v60, 0, v60
	v_max_f32_e32 v61, 0, v61
	v_pk_mul_f32 v[70:71], v[56:57], v[56:57]
	v_max_f32_e32 v56, 0, v62
; __device__ __forceinline__ unsigned pk2(float lo, float hi) { const f32x2 v = (f32x2){lo, hi}; const bf16x2_t b = __builtin_convertvector(v, bf16x2_t); return __builtin_bit_cast(unsigned, b); }
; #define PG8_WAIT_V(n) asm volatile("s_waitcnt vmcnt(" #n ")" ::: "memory")
; #define PG8_BAR __builtin_amdgcn_s_barrier()
;     __device__ __forceinline__ void operator()(const f32x4 (&acc)[2][2][4][2], const Unit& u, int wr, int wc, int fr, int fq, const float (&)[8]) const {
;     ...
;         for (int ai = 0; ai < 2; ++ai)
; #pragma unroll
;             for (int m = 0; m < 4; ++m) { const int row = row0 + ai * HALF + m * 16; const float rs = rsqrtf(ep[ai * 4 + m] * (1.0f / 1024.0f) + EPS);
;                 u16* rowp = O + (size_t)row * ldc + col0;
; #pragma unroll
;                 for (int bj = 0; bj < 2; ++bj) { f32x4 v0 = acc[ai][bj][m][0] * rs, v1 = acc[ai][bj][m][1] * rs;
;                     if (ACT == 1) {
; #pragma unroll
;                         for (int j = 0; j < 4; ++j) { const float a0 = fmaxf(v0[j], 0.f), a1 = fmaxf(v1[j], 0.f); v0[j] = a0 * a0; v1[j] = a1 * a1; } }
;                     u32x4 w; w.x = pk2(v0[0], v0[1]); w.y = pk2(v0[2], v0[3]); w.z = pk2(v1[0], v1[1]); w.w = pk2(v1[2], v1[3]);
;                     *(u32x4*)(rowp + bj * HALF) = w; } }
; template <class Epi>
; __device__ __forceinline__ void gemm_phase(LAS unsigned char* lds, const Gemm g, const StaticOrder& S, const Epi& E) {
;     ...
;         if (!has_next) break;
; #pragma unroll
;         for (int a = 0; a < 2; ++a)
; #pragma unroll
;             for (int b = 0; b < 2; ++b)
; #pragma unroll
;                 for (int m = 0; m < 4; ++m)
; #pragma unroll
;                     for (int n = 0; n < 2; ++n) acc[a][b][m][n] = (f32x4){0.f, 0.f, 0.f, 0.f};
;         cur = nxt; cA = nA; cB = nB; ++ui;
;     }
;     PG8_WAIT_V(0);
;     if (wr == 0) PG8_BAR;
	v_max_f32_e32 v58, 0, v58
	v_max_f32_e32 v57, 0, v63
	v_max_f32_e32 v59, 0, v59
	v_pk_mul_f32 v[60:61], v[60:61], v[60:61]
	v_pk_mul_f32 v[62:63], v[56:57], v[56:57]
	v_pk_mul_f32 v[72:73], v[58:59], v[58:59]
	v_pk_mul_f32 v[50:51], v[50:51], v[68:69] op_sel_hi:[1,0]
	v_cvt_pk_bf16_f32 v56, v60, v61
	v_cvt_pk_bf16_f32 v57, v62, v63
	v_cvt_pk_bf16_f32 v58, v70, v71
	v_cvt_pk_bf16_f32 v59, v72, v73
	v_pk_mul_f32 v[52:53], v[52:53], v[68:69] op_sel_hi:[1,0]
	v_pk_mul_f32 v[48:49], v[48:49], v[68:69] op_sel_hi:[1,0]
	v_max_f32_e32 v50, 0, v50
	v_max_f32_e32 v51, 0, v51
	global_store_dwordx4 v[66:67], v[56:59], off
	v_pk_mul_f32 v[54:55], v[54:55], v[68:69] op_sel_hi:[1,0]
	v_max_f32_e32 v52, 0, v52
	v_max_f32_e32 v48, 0, v48
	v_max_f32_e32 v53, 0, v53
	v_max_f32_e32 v49, 0, v49
	v_pk_mul_f32 v[58:59], v[50:51], v[50:51]
	v_pk_mul_f32 v[52:53], v[52:53], v[52:53]
	v_pk_mul_f32 v[56:57], v[48:49], v[48:49]
	v_max_f32_e32 v48, 0, v54
	v_max_f32_e32 v49, 0, v55
	v_pk_mul_f32 v[54:55], v[48:49], v[48:49]
	v_cvt_pk_bf16_f32 v48, v52, v53
	v_cvt_pk_bf16_f32 v49, v54, v55
	v_cvt_pk_bf16_f32 v50, v56, v57
	v_cvt_pk_bf16_f32 v51, v58, v59
	global_store_dwordx4 v[66:67], v[48:51], off offset:256
	s_nop 1
	v_mov_b32_e32 v48, v233
	v_pk_mul_f32 v[40:41], v[40:41], v[48:49] op_sel_hi:[1,0]
	v_pk_mul_f32 v[46:47], v[46:47], v[48:49] op_sel_hi:[1,0]
	v_pk_mul_f32 v[44:45], v[44:45], v[48:49] op_sel_hi:[1,0]
	v_pk_mul_f32 v[42:43], v[42:43], v[48:49] op_sel_hi:[1,0]
	v_max_f32_e32 v40, 0, v40
	v_max_f32_e32 v41, 0, v41
	v_max_f32_e32 v44, 0, v44
	v_max_f32_e32 v45, 0, v45
	v_pk_mul_f32 v[52:53], v[40:41], v[40:41]
	v_max_f32_e32 v40, 0, v46
	v_max_f32_e32 v42, 0, v42
	v_max_f32_e32 v41, 0, v47
	v_max_f32_e32 v43, 0, v43
	v_pk_mul_f32 v[44:45], v[44:45], v[44:45]
	v_pk_mul_f32 v[46:47], v[40:41], v[40:41]
	v_pk_mul_f32 v[54:55], v[42:43], v[42:43]
	v_pk_mul_f32 v[32:33], v[32:33], v[48:49] op_sel_hi:[1,0]
	v_lshl_add_u64 v[50:51], v[66:67], 0, s[24:25]
	v_cvt_pk_bf16_f32 v40, v44, v45
	v_cvt_pk_bf16_f32 v41, v46, v47
	v_cvt_pk_bf16_f32 v42, v52, v53
	v_cvt_pk_bf16_f32 v43, v54, v55
	v_pk_mul_f32 v[38:39], v[38:39], v[48:49] op_sel_hi:[1,0]
	v_max_f32_e32 v32, 0, v32
	v_max_f32_e32 v33, 0, v33
	global_store_dwordx4 v[50:51], v[40:43], off
	v_pk_mul_f32 v[36:37], v[36:37], v[48:49] op_sel_hi:[1,0]
	v_pk_mul_f32 v[34:35], v[34:35], v[48:49] op_sel_hi:[1,0]
	v_pk_mul_f32 v[40:41], v[32:33], v[32:33]
	v_max_f32_e32 v32, 0, v38
	v_max_f32_e32 v33, 0, v39
	v_max_f32_e32 v36, 0, v36
	v_max_f32_e32 v37, 0, v37
	v_pk_mul_f32 v[36:37], v[36:37], v[36:37]
	v_pk_mul_f32 v[44:45], v[32:33], v[32:33]
	v_cvt_pk_bf16_f32 v32, v36, v37
	v_max_f32_e32 v34, 0, v34
	v_max_f32_e32 v35, 0, v35
	v_pk_mul_f32 v[46:47], v[34:35], v[34:35]
	v_cvt_pk_bf16_f32 v33, v44, v45
	v_cvt_pk_bf16_f32 v34, v40, v41
	v_cvt_pk_bf16_f32 v35, v46, v47
	global_store_dwordx4 v[50:51], v[32:35], off offset:256
	s_nop 1
	v_lshl_add_u64 v[34:35], v[50:51], 0, s[24:25]
	v_mov_b32_e32 v36, v234
	v_pk_mul_f32 v[24:25], v[24:25], v[36:37] op_sel_hi:[1,0]
	v_pk_mul_f32 v[30:31], v[30:31], v[36:37] op_sel_hi:[1,0]
	v_pk_mul_f32 v[28:29], v[28:29], v[36:37] op_sel_hi:[1,0]
	v_pk_mul_f32 v[26:27], v[26:27], v[36:37] op_sel_hi:[1,0]
	v_max_f32_e32 v24, 0, v24
	v_max_f32_e32 v25, 0, v25
	v_max_f32_e32 v28, 0, v28
	v_max_f32_e32 v29, 0, v29
	v_pk_mul_f32 v[38:39], v[24:25], v[24:25]
	v_max_f32_e32 v24, 0, v30
	v_max_f32_e32 v26, 0, v26
	v_max_f32_e32 v25, 0, v31
	v_max_f32_e32 v27, 0, v27
	v_pk_mul_f32 v[28:29], v[28:29], v[28:29]
	v_pk_mul_f32 v[30:31], v[24:25], v[24:25]
	v_pk_mul_f32 v[40:41], v[26:27], v[26:27]
	v_pk_mul_f32 v[18:19], v[18:19], v[36:37] op_sel_hi:[1,0]
	v_cvt_pk_bf16_f32 v24, v28, v29
	v_cvt_pk_bf16_f32 v25, v30, v31
	v_cvt_pk_bf16_f32 v26, v38, v39
	v_cvt_pk_bf16_f32 v27, v40, v41
	v_pk_mul_f32 v[20:21], v[20:21], v[36:37] op_sel_hi:[1,0]
	v_pk_mul_f32 v[16:17], v[16:17], v[36:37] op_sel_hi:[1,0]
	v_max_f32_e32 v18, 0, v18
	v_max_f32_e32 v19, 0, v19
	global_store_dwordx4 v[34:35], v[24:27], off
	v_pk_mul_f32 v[22:23], v[22:23], v[36:37] op_sel_hi:[1,0]
	v_max_f32_e32 v20, 0, v20
	v_max_f32_e32 v16, 0, v16
	v_max_f32_e32 v21, 0, v21
	v_max_f32_e32 v17, 0, v17
	v_pk_mul_f32 v[26:27], v[18:19], v[18:19]
	v_pk_mul_f32 v[20:21], v[20:21], v[20:21]
	v_pk_mul_f32 v[24:25], v[16:17], v[16:17]
	v_max_f32_e32 v16, 0, v22
	v_max_f32_e32 v17, 0, v23
	v_pk_mul_f32 v[22:23], v[16:17], v[16:17]
	v_cvt_pk_bf16_f32 v16, v20, v21
	v_cvt_pk_bf16_f32 v17, v22, v23
	v_cvt_pk_bf16_f32 v18, v24, v25
	v_cvt_pk_bf16_f32 v19, v26, v27
	global_store_dwordx4 v[34:35], v[16:19], off offset:256
	s_nop 1
	v_mov_b32_e32 v16, v235
	v_pk_mul_f32 v[8:9], v[8:9], v[16:17] op_sel_hi:[1,0]
	v_pk_mul_f32 v[14:15], v[14:15], v[16:17] op_sel_hi:[1,0]
	v_pk_mul_f32 v[12:13], v[12:13], v[16:17] op_sel_hi:[1,0]
	v_pk_mul_f32 v[10:11], v[10:11], v[16:17] op_sel_hi:[1,0]
	v_max_f32_e32 v8, 0, v8
	v_max_f32_e32 v9, 0, v9
	v_max_f32_e32 v12, 0, v12
	v_max_f32_e32 v13, 0, v13
	v_pk_mul_f32 v[20:21], v[8:9], v[8:9]
	v_max_f32_e32 v8, 0, v14
	v_max_f32_e32 v10, 0, v10
	v_max_f32_e32 v9, 0, v15
	v_max_f32_e32 v11, 0, v11
	v_pk_mul_f32 v[12:13], v[12:13], v[12:13]
	v_pk_mul_f32 v[14:15], v[8:9], v[8:9]
	v_pk_mul_f32 v[22:23], v[10:11], v[10:11]
	v_pk_mul_f32 v[0:1], v[0:1], v[16:17] op_sel_hi:[1,0]
	v_lshl_add_u64 v[18:19], v[34:35], 0, s[24:25]
	v_cvt_pk_bf16_f32 v8, v12, v13
	v_cvt_pk_bf16_f32 v9, v14, v15
	v_cvt_pk_bf16_f32 v10, v20, v21
	v_cvt_pk_bf16_f32 v11, v22, v23
	v_pk_mul_f32 v[6:7], v[6:7], v[16:17] op_sel_hi:[1,0]
	v_pk_mul_f32 v[4:5], v[4:5], v[16:17] op_sel_hi:[1,0]
	v_pk_mul_f32 v[2:3], v[2:3], v[16:17] op_sel_hi:[1,0]
	v_max_f32_e32 v0, 0, v0
	v_max_f32_e32 v1, 0, v1
	global_store_dwordx4 v[18:19], v[8:11], off
	v_max_f32_e32 v4, 0, v4
	v_max_f32_e32 v5, 0, v5
	v_pk_mul_f32 v[8:9], v[0:1], v[0:1]
	v_max_f32_e32 v0, 0, v6
	v_max_f32_e32 v2, 0, v2
	v_max_f32_e32 v1, 0, v7
	v_max_f32_e32 v3, 0, v3
	v_pk_mul_f32 v[4:5], v[4:5], v[4:5]
	v_pk_mul_f32 v[6:7], v[0:1], v[0:1]
	v_pk_mul_f32 v[10:11], v[2:3], v[2:3]
	v_cvt_pk_bf16_f32 v0, v4, v5
	v_cvt_pk_bf16_f32 v1, v6, v7
	v_cvt_pk_bf16_f32 v2, v8, v9
	v_cvt_pk_bf16_f32 v3, v10, v11
	s_and_b64 vcc, exec, s[0:1]
	global_store_dwordx4 v[18:19], v[0:3], off offset:256
	s_cbranch_vccz .LBB0_763
	s_waitcnt vmcnt(0)
	s_cmpk_gt_u32 s9, 0xff
	s_cbranch_scc1 .LBB0_774
	s_barrier

; #define PG8_STAGE(bufoff, gbase, voff) do { _Pragma("unroll") for (int _i = 0; _i < 2; ++_i) \
;         __builtin_amdgcn_global_load_lds((const unsigned*)((const char*)(gbase) + (voff)[_i]), (LAS unsigned*)(lds + (bufoff) + ldsw + _i * 8192), 16, 0, 0); } while (0)
; #define PG8_LDA(dst, b, h) do { _Pragma("unroll") for (int m = 0; m < 4; ++m) _Pragma("unroll") for (int k = 0; k < 2; ++k) dst[m][k] = *(const LAS bf16x8*)(lds + PG8_SA(b, h) + aoff + m * 2048 + k * 1024); } while (0)
; #define PG8_LDB(dst, b, h) do { _Pragma("unroll") for (int n = 0; n < 2; ++n) _Pragma("unroll") for (int k = 0; k < 2; ++k) dst[n][k] = *(const LAS bf16x8*)(lds + PG8_SB(b, h) + boff + n * 2048 + k * 1024); } while (0)
; #define PG8_MMA(ai, bj, At, Bt) do { __builtin_amdgcn_s_setprio(1); _Pragma("unroll") for (int m = 0; m < 4; ++m) _Pragma("unroll") for (int n = 0; n < 2; ++n) _Pragma("unroll") for (int k = 0; k < 2; ++k) \
;         acc[ai][bj][m][n] = __builtin_amdgcn_mfma_f32_16x16x32_bf16(Bt[n][k], At[m][k], acc[ai][bj][m][n], 0, 0, 0); __builtin_amdgcn_s_setprio(0); } while (0)
; #define PG8_WAIT_V(n) asm volatile("s_waitcnt vmcnt(" #n ")" ::: "memory")
; #define PG8_WAIT_L(n) asm volatile("s_waitcnt lgkmcnt(" #n ")" ::: "memory")
; #define PG8_BAR __builtin_amdgcn_s_barrier()
; #define PG8_SCHED __builtin_amdgcn_sched_barrier(0)
; template <class Epi>
; __device__ __forceinline__ void gemm_phase(LAS unsigned char* lds, const Gemm g, const StaticOrder& S, const Epi& E) {
;     ...
;             PG8_LDB(B0, 0, 0); PG8_SCHED; PG8_LDA(At, 0, 0); PG8_STAGE(PG8_SA(1, 1), a1 + hstepA, voffA);
;             PG8_WAIT_L(8); PG8_BAR; PG8_WAIT_L(0); PG8_MMA(0, 0, At, B0); PG8_BAR; PG8_SCHED;
;             PG8_LDB(B1, 0, 1); PG8_STAGE(PG8_SB(0, 0), b2, voffB);
;             PG8_BAR; PG8_WAIT_L(0); PG8_MMA(0, 1, At, B1); PG8_BAR;
;             PG8_LDA(At, 0, 1); PG8_STAGE(PG8_SA(0, 0), a2, voffA);
;             PG8_BAR; PG8_WAIT_L(0); PG8_MMA(1, 0, At, B0); PG8_BAR; PG8_SCHED;
;             PG8_STAGE(PG8_SB(0, 1), b2 + hstepB, voffB);
;             PG8_WAIT_V(6); PG8_BAR; PG8_MMA(1, 1, At, B1); PG8_BAR;
.LBB0_922:
	ds_read_b128 v[146:149], v173
	ds_read_b128 v[154:157], v173 offset:1024
	ds_read_b128 v[158:161], v173 offset:2048
	ds_read_b128 v[162:165], v173 offset:3072
	s_add_u32 s22, s20, 0xfffc0080
	s_addc_u32 s23, s21, -1
	s_cmp_eq_u32 s47, 12
	s_cselect_b32 s25, s13, s23
	s_cselect_b32 s24, s43, s22
	s_cselect_b32 s23, s11, s46
	s_cselect_b32 s22, s44, s45
	v_lshl_add_u64 v[150:151], s[20:21], 0, v[138:139]
	s_add_i32 m0, s19, 0xc000
	ds_read_b128 v[166:169], v174
	ds_read_b128 v[178:181], v174 offset:1024
	ds_read_b128 v[182:185], v174 offset:2048
	ds_read_b128 v[186:189], v174 offset:3072
	ds_read_b128 v[190:193], v174 offset:4096
	ds_read_b128 v[194:197], v174 offset:5120
	ds_read_b128 v[198:201], v174 offset:6144
	ds_read_b128 v[202:205], v174 offset:7168
	global_load_lds_dwordx4 v[150:151], off
	v_lshl_add_u64 v[150:151], s[20:21], 0, v[140:141]
	s_add_i32 m0, s19, 0xe000
	s_nop 0
	global_load_lds_dwordx4 v[150:151], off
	s_waitcnt lgkmcnt(8)
	s_barrier
	s_waitcnt lgkmcnt(0)
	s_setprio 1
	s_waitcnt lgkmcnt(0)
	v_mfma_f32_16x16x32_bf16 v[124:127], v[146:149], v[166:169], v[124:127]
	v_mfma_f32_16x16x32_bf16 v[120:123], v[158:161], v[166:169], v[120:123]
	v_mfma_f32_16x16x32_bf16 v[112:115], v[146:149], v[182:185], v[112:115]
	v_mfma_f32_16x16x32_bf16 v[104:107], v[158:161], v[182:185], v[104:107]
	v_mfma_f32_16x16x32_bf16 v[92:95], v[146:149], v[190:193], v[92:95]
	v_mfma_f32_16x16x32_bf16 v[88:91], v[158:161], v[190:193], v[88:91]
	v_mfma_f32_16x16x32_bf16 v[80:83], v[146:149], v[198:201], v[80:83]
	v_mfma_f32_16x16x32_bf16 v[72:75], v[158:161], v[198:201], v[72:75]
	v_mfma_f32_16x16x32_bf16 v[124:127], v[154:157], v[178:181], v[124:127]
	v_mfma_f32_16x16x32_bf16 v[120:123], v[162:165], v[178:181], v[120:123]
	v_mfma_f32_16x16x32_bf16 v[112:115], v[154:157], v[186:189], v[112:115]
	v_mfma_f32_16x16x32_bf16 v[104:107], v[162:165], v[186:189], v[104:107]
	v_mfma_f32_16x16x32_bf16 v[92:95], v[154:157], v[194:197], v[92:95]
	v_mfma_f32_16x16x32_bf16 v[88:91], v[162:165], v[194:197], v[88:91]
	v_mfma_f32_16x16x32_bf16 v[80:83], v[154:157], v[202:205], v[80:83]
	v_mfma_f32_16x16x32_bf16 v[72:75], v[162:165], v[202:205], v[72:75]
	s_setprio 0
	s_barrier
	s_add_i32 s48, s38, s27
	v_lshl_add_u64 v[150:151], s[22:23], 0, v[132:133]
	s_mov_b32 m0, s48
	ds_read_b128 v[206:209], v175
	ds_read_b128 v[210:213], v175 offset:1024
	ds_read_b128 v[214:217], v175 offset:2048
	ds_read_b128 v[218:221], v175 offset:3072
	global_load_lds_dwordx4 v[150:151], off
	v_lshl_add_u64 v[222:223], s[22:23], 0, v[128:129]
	s_add_i32 m0, s48, 0x2000
	s_nop 0
	global_load_lds_dwordx4 v[222:223], off
	s_barrier
	s_waitcnt lgkmcnt(0)
	s_setprio 1
	s_waitcnt lgkmcnt(0)
	v_mfma_f32_16x16x32_bf16 v[116:119], v[206:209], v[166:169], v[116:119]
	v_mfma_f32_16x16x32_bf16 v[108:111], v[214:217], v[166:169], v[108:111]
	v_mfma_f32_16x16x32_bf16 v[100:103], v[206:209], v[182:185], v[100:103]
	v_mfma_f32_16x16x32_bf16 v[96:99], v[214:217], v[182:185], v[96:99]
	v_mfma_f32_16x16x32_bf16 v[84:87], v[206:209], v[190:193], v[84:87]
	v_mfma_f32_16x16x32_bf16 v[76:79], v[214:217], v[190:193], v[76:79]
	v_mfma_f32_16x16x32_bf16 v[68:71], v[206:209], v[198:201], v[68:71]
	v_mfma_f32_16x16x32_bf16 v[64:67], v[214:217], v[198:201], v[64:67]
	v_mfma_f32_16x16x32_bf16 v[116:119], v[210:213], v[178:181], v[116:119]
	v_mfma_f32_16x16x32_bf16 v[108:111], v[218:221], v[178:181], v[108:111]
	v_mfma_f32_16x16x32_bf16 v[100:103], v[210:213], v[186:189], v[100:103]
	v_mfma_f32_16x16x32_bf16 v[96:99], v[218:221], v[186:189], v[96:99]
	v_mfma_f32_16x16x32_bf16 v[84:87], v[210:213], v[194:197], v[84:87]
	v_mfma_f32_16x16x32_bf16 v[76:79], v[218:221], v[194:197], v[76:79]
	v_mfma_f32_16x16x32_bf16 v[68:71], v[210:213], v[202:205], v[68:71]
	v_mfma_f32_16x16x32_bf16 v[64:67], v[218:221], v[202:205], v[64:67]
	s_setprio 0
	s_mov_b32 m0, s19
	v_lshl_add_u64 v[224:225], s[24:25], 0, v[134:135]
	s_barrier
	ds_read_b128 v[166:169], v174 offset:16384
	ds_read_b128 v[178:181], v174 offset:17408
	ds_read_b128 v[182:185], v174 offset:18432
	ds_read_b128 v[186:189], v174 offset:19456
	ds_read_b128 v[190:193], v174 offset:20480
	ds_read_b128 v[194:197], v174 offset:21504
	ds_read_b128 v[198:201], v174 offset:22528
	ds_read_b128 v[202:205], v174 offset:23552
	global_load_lds_dwordx4 v[224:225], off
	v_lshl_add_u64 v[226:227], s[24:25], 0, v[130:131]
	s_mov_b32 m0, s30
	s_nop 0
	global_load_lds_dwordx4 v[226:227], off
	s_barrier
	s_waitcnt lgkmcnt(0)
	s_setprio 1
	s_waitcnt lgkmcnt(0)
	v_mfma_f32_16x16x32_bf16 v[60:63], v[146:149], v[166:169], v[60:63]
	v_mfma_f32_16x16x32_bf16 v[56:59], v[158:161], v[166:169], v[56:59]
	v_mfma_f32_16x16x32_bf16 v[48:51], v[146:149], v[182:185], v[48:51]
	v_mfma_f32_16x16x32_bf16 v[40:43], v[158:161], v[182:185], v[40:43]
	v_mfma_f32_16x16x32_bf16 v[32:35], v[146:149], v[190:193], v[32:35]
	v_mfma_f32_16x16x32_bf16 v[24:27], v[158:161], v[190:193], v[24:27]
	v_mfma_f32_16x16x32_bf16 v[16:19], v[146:149], v[198:201], v[16:19]
	v_mfma_f32_16x16x32_bf16 v[8:11], v[158:161], v[198:201], v[8:11]
	v_mfma_f32_16x16x32_bf16 v[60:63], v[154:157], v[178:181], v[60:63]
	v_mfma_f32_16x16x32_bf16 v[56:59], v[162:165], v[178:181], v[56:59]
	v_mfma_f32_16x16x32_bf16 v[48:51], v[154:157], v[186:189], v[48:51]
	v_mfma_f32_16x16x32_bf16 v[40:43], v[162:165], v[186:189], v[40:43]
	v_mfma_f32_16x16x32_bf16 v[32:35], v[154:157], v[194:197], v[32:35]
	v_mfma_f32_16x16x32_bf16 v[24:27], v[162:165], v[194:197], v[24:27]
	v_mfma_f32_16x16x32_bf16 v[16:19], v[154:157], v[202:205], v[16:19]
	v_mfma_f32_16x16x32_bf16 v[8:11], v[162:165], v[202:205], v[8:11]
	s_setprio 0
	s_barrier
; #define PG8_STAGE(bufoff, gbase, voff) do { _Pragma("unroll") for (int _i = 0; _i < 2; ++_i) \
;         __builtin_amdgcn_global_load_lds((const unsigned*)((const char*)(gbase) + (voff)[_i]), (LAS unsigned*)(lds + (bufoff) + ldsw + _i * 8192), 16, 0, 0); } while (0)
; #define PG8_LDA(dst, b, h) do { _Pragma("unroll") for (int m = 0; m < 4; ++m) _Pragma("unroll") for (int k = 0; k < 2; ++k) dst[m][k] = *(const LAS bf16x8*)(lds + PG8_SA(b, h) + aoff + m * 2048 + k * 1024); } while (0)
; #define PG8_LDB(dst, b, h) do { _Pragma("unroll") for (int n = 0; n < 2; ++n) _Pragma("unroll") for (int k = 0; k < 2; ++k) dst[n][k] = *(const LAS bf16x8*)(lds + PG8_SB(b, h) + boff + n * 2048 + k * 1024); } while (0)
; #define PG8_MMA(ai, bj, At, Bt) do { __builtin_amdgcn_s_setprio(1); _Pragma("unroll") for (int m = 0; m < 4; ++m) _Pragma("unroll") for (int n = 0; n < 2; ++n) _Pragma("unroll") for (int k = 0; k < 2; ++k) \
;         acc[ai][bj][m][n] = __builtin_amdgcn_mfma_f32_16x16x32_bf16(Bt[n][k], At[m][k], acc[ai][bj][m][n], 0, 0, 0); __builtin_amdgcn_s_setprio(0); } while (0)
; #define PG8_WAIT_V(n) asm volatile("s_waitcnt vmcnt(" #n ")" ::: "memory")
; #define PG8_WAIT_L(n) asm volatile("s_waitcnt lgkmcnt(" #n ")" ::: "memory")
; #define PG8_BAR __builtin_amdgcn_s_barrier()
; #define PG8_SCHED __builtin_amdgcn_sched_barrier(0)
; template <class Epi>
; __device__ __forceinline__ void gemm_phase(LAS unsigned char* lds, const Gemm g, const StaticOrder& S, const Epi& E) {
;     ...
;             PG8_WAIT_V(6); PG8_BAR; PG8_MMA(1, 1, At, B1); PG8_BAR;
;             PG8_LDB(B0, 1, 0); PG8_SCHED; PG8_LDA(At, 1, 0); PG8_STAGE(PG8_SA(0, 1), a2 + hstepA, voffA);
;             PG8_WAIT_L(8); PG8_BAR; PG8_WAIT_L(0); PG8_MMA(0, 0, At, B0); PG8_BAR; PG8_SCHED;
;             PG8_LDB(B1, 1, 1); PG8_STAGE(PG8_SB(1, 0), b3, voffB);
;             PG8_BAR; PG8_WAIT_L(0); PG8_MMA(0, 1, At, B1); PG8_BAR;
;             PG8_LDA(At, 1, 1); PG8_STAGE(PG8_SA(1, 0), a3, voffA);
;             PG8_BAR; PG8_WAIT_L(0); PG8_MMA(1, 0, At, B0); PG8_BAR; PG8_SCHED;
	s_add_u32 s48, s22, 0x40000
	s_addc_u32 s49, s23, 0
	s_add_i32 s50, s39, s27
	v_lshl_add_u64 v[146:147], s[48:49], 0, v[132:133]
	s_mov_b32 m0, s50
	s_nop 0
	global_load_lds_dwordx4 v[146:147], off
	v_lshl_add_u64 v[146:147], s[48:49], 0, v[128:129]
	s_add_i32 m0, s50, 0x2000
	s_nop 0
	global_load_lds_dwordx4 v[146:147], off
	s_waitcnt vmcnt(6)
	s_barrier
	s_setprio 1
	v_mfma_f32_16x16x32_bf16 v[52:55], v[206:209], v[166:169], v[52:55]
	v_mfma_f32_16x16x32_bf16 v[44:47], v[214:217], v[166:169], v[44:47]
	v_mfma_f32_16x16x32_bf16 v[36:39], v[206:209], v[182:185], v[36:39]
	v_mfma_f32_16x16x32_bf16 v[28:31], v[214:217], v[182:185], v[28:31]
	v_mfma_f32_16x16x32_bf16 v[20:23], v[206:209], v[190:193], v[20:23]
	v_mfma_f32_16x16x32_bf16 v[12:15], v[214:217], v[190:193], v[12:15]
	v_mfma_f32_16x16x32_bf16 v[4:7], v[206:209], v[198:201], v[4:7]
	v_mfma_f32_16x16x32_bf16 v[0:3], v[214:217], v[198:201], v[0:3]
	v_mfma_f32_16x16x32_bf16 v[52:55], v[210:213], v[178:181], v[52:55]
	v_mfma_f32_16x16x32_bf16 v[44:47], v[218:221], v[178:181], v[44:47]
	v_mfma_f32_16x16x32_bf16 v[36:39], v[210:213], v[186:189], v[36:39]
	v_mfma_f32_16x16x32_bf16 v[28:31], v[218:221], v[186:189], v[28:31]
	v_mfma_f32_16x16x32_bf16 v[20:23], v[210:213], v[194:197], v[20:23]
	v_mfma_f32_16x16x32_bf16 v[12:15], v[218:221], v[194:197], v[12:15]
	v_mfma_f32_16x16x32_bf16 v[4:7], v[210:213], v[202:205], v[4:7]
	v_mfma_f32_16x16x32_bf16 v[0:3], v[218:221], v[202:205], v[0:3]
	s_setprio 0
	s_add_i32 s48, 0, 0x18000
	v_add_u32_e32 v162, s48, v171
	s_barrier
	ds_read_b128 v[146:149], v162
	ds_read_b128 v[154:157], v162 offset:1024
	ds_read_b128 v[158:161], v162 offset:2048
	ds_read_b128 v[162:165], v162 offset:3072
	s_add_u32 s24, s24, 0x40000
	s_addc_u32 s25, s25, 0
	s_mov_b32 m0, s31
	v_lshl_add_u64 v[206:207], s[24:25], 0, v[134:135]
	ds_read_b128 v[166:169], v174 offset:32768
	ds_read_b128 v[178:181], v174 offset:33792
	ds_read_b128 v[182:185], v174 offset:34816
	ds_read_b128 v[186:189], v174 offset:35840
	ds_read_b128 v[190:193], v174 offset:36864
	ds_read_b128 v[194:197], v174 offset:37888
	ds_read_b128 v[198:201], v174 offset:38912
	ds_read_b128 v[202:205], v174 offset:39936
	global_load_lds_dwordx4 v[206:207], off
	v_lshl_add_u64 v[206:207], s[24:25], 0, v[130:131]
	s_mov_b32 m0, s33
	s_nop 0
	global_load_lds_dwordx4 v[206:207], off
	s_waitcnt lgkmcnt(8)
	s_barrier
	s_waitcnt lgkmcnt(0)
	s_setprio 1
	s_waitcnt lgkmcnt(0)
	v_mfma_f32_16x16x32_bf16 v[124:127], v[146:149], v[166:169], v[124:127]
	v_mfma_f32_16x16x32_bf16 v[120:123], v[158:161], v[166:169], v[120:123]
	v_mfma_f32_16x16x32_bf16 v[112:115], v[146:149], v[182:185], v[112:115]
	v_mfma_f32_16x16x32_bf16 v[104:107], v[158:161], v[182:185], v[104:107]
	v_mfma_f32_16x16x32_bf16 v[92:95], v[146:149], v[190:193], v[92:95]
	v_mfma_f32_16x16x32_bf16 v[88:91], v[158:161], v[190:193], v[88:91]
	v_mfma_f32_16x16x32_bf16 v[80:83], v[146:149], v[198:201], v[80:83]
	v_mfma_f32_16x16x32_bf16 v[72:75], v[158:161], v[198:201], v[72:75]
	v_mfma_f32_16x16x32_bf16 v[124:127], v[154:157], v[178:181], v[124:127]
	v_mfma_f32_16x16x32_bf16 v[120:123], v[162:165], v[178:181], v[120:123]
	v_mfma_f32_16x16x32_bf16 v[112:115], v[154:157], v[186:189], v[112:115]
	v_mfma_f32_16x16x32_bf16 v[104:107], v[162:165], v[186:189], v[104:107]
	v_mfma_f32_16x16x32_bf16 v[92:95], v[154:157], v[194:197], v[92:95]
	v_mfma_f32_16x16x32_bf16 v[88:91], v[162:165], v[194:197], v[88:91]
	v_mfma_f32_16x16x32_bf16 v[80:83], v[154:157], v[202:205], v[80:83]
	v_mfma_f32_16x16x32_bf16 v[72:75], v[162:165], v[202:205], v[72:75]
	s_setprio 0
	s_barrier
	s_add_i32 s24, 0, 0x1c000
	s_add_i32 s25, s48, s27
	v_add_u32_e32 v177, s24, v171
	v_lshl_add_u64 v[150:151], v[150:151], 0, s[4:5]
	s_mov_b32 m0, s25
	ds_read_b128 v[206:209], v177
	ds_read_b128 v[210:213], v177 offset:1024
	ds_read_b128 v[214:217], v177 offset:2048
	ds_read_b128 v[218:221], v177 offset:3072
	global_load_lds_dwordx4 v[150:151], off
	v_lshl_add_u64 v[150:151], v[222:223], 0, s[4:5]
	s_add_i32 m0, s25, 0x2000
	s_nop 0
	global_load_lds_dwordx4 v[150:151], off
	s_barrier
	s_waitcnt lgkmcnt(0)
	s_setprio 1
	s_waitcnt lgkmcnt(0)
	v_mfma_f32_16x16x32_bf16 v[116:119], v[206:209], v[166:169], v[116:119]
	v_mfma_f32_16x16x32_bf16 v[108:111], v[214:217], v[166:169], v[108:111]
	v_mfma_f32_16x16x32_bf16 v[100:103], v[206:209], v[182:185], v[100:103]
	v_mfma_f32_16x16x32_bf16 v[96:99], v[214:217], v[182:185], v[96:99]
	v_mfma_f32_16x16x32_bf16 v[84:87], v[206:209], v[190:193], v[84:87]
	v_mfma_f32_16x16x32_bf16 v[76:79], v[214:217], v[190:193], v[76:79]
	v_mfma_f32_16x16x32_bf16 v[68:71], v[206:209], v[198:201], v[68:71]
	v_mfma_f32_16x16x32_bf16 v[64:67], v[214:217], v[198:201], v[64:67]
	v_mfma_f32_16x16x32_bf16 v[116:119], v[210:213], v[178:181], v[116:119]
	v_mfma_f32_16x16x32_bf16 v[108:111], v[218:221], v[178:181], v[108:111]
	v_mfma_f32_16x16x32_bf16 v[100:103], v[210:213], v[186:189], v[100:103]
	v_mfma_f32_16x16x32_bf16 v[96:99], v[218:221], v[186:189], v[96:99]
	v_mfma_f32_16x16x32_bf16 v[84:87], v[210:213], v[194:197], v[84:87]
	v_mfma_f32_16x16x32_bf16 v[76:79], v[218:221], v[194:197], v[76:79]
	v_mfma_f32_16x16x32_bf16 v[68:71], v[210:213], v[202:205], v[68:71]
	v_mfma_f32_16x16x32_bf16 v[64:67], v[218:221], v[202:205], v[64:67]
	s_setprio 0
	s_mov_b32 m0, s35
	v_lshl_add_u64 v[150:151], v[224:225], 0, s[4:5]
	s_barrier
	ds_read_b128 v[166:169], v174 offset:49152
	ds_read_b128 v[178:181], v174 offset:50176
	ds_read_b128 v[182:185], v174 offset:51200
	ds_read_b128 v[186:189], v174 offset:52224
	ds_read_b128 v[190:193], v174 offset:53248
	ds_read_b128 v[194:197], v174 offset:54272
	ds_read_b128 v[198:201], v174 offset:55296
	ds_read_b128 v[202:205], v174 offset:56320
	global_load_lds_dwordx4 v[150:151], off
	v_lshl_add_u64 v[150:151], v[226:227], 0, s[4:5]
	s_mov_b32 m0, s36
	s_nop 0
	global_load_lds_dwordx4 v[150:151], off
	s_barrier
; __device__ __forceinline__ unsigned pk2(float lo, float hi) { const f32x2 v = (f32x2){lo, hi}; const bf16x2_t b = __builtin_convertvector(v, bf16x2_t); return __builtin_bit_cast(unsigned, b); }
; #define PG8_STAGE(bufoff, gbase, voff) do { _Pragma("unroll") for (int _i = 0; _i < 2; ++_i) \
;         __builtin_amdgcn_global_load_lds((const unsigned*)((const char*)(gbase) + (voff)[_i]), (LAS unsigned*)(lds + (bufoff) + ldsw + _i * 8192), 16, 0, 0); } while (0)
; #define PG8_MMA(ai, bj, At, Bt) do { __builtin_amdgcn_s_setprio(1); _Pragma("unroll") for (int m = 0; m < 4; ++m) _Pragma("unroll") for (int n = 0; n < 2; ++n) _Pragma("unroll") for (int k = 0; k < 2; ++k) \
;         acc[ai][bj][m][n] = __builtin_amdgcn_mfma_f32_16x16x32_bf16(Bt[n][k], At[m][k], acc[ai][bj][m][n], 0, 0, 0); __builtin_amdgcn_s_setprio(0); } while (0)
; #define PG8_WAIT_V(n) asm volatile("s_waitcnt vmcnt(" #n ")" ::: "memory")
;     __device__ __forceinline__ void operator()(const f32x4 (&acc)[2][2][4][2], const Unit& u, int wr, int wc, int fr, int fq, const float (&)[8]) const {
;     ...
;         const int col0 = u.pn * BM + wc * 32 + 8 * fq;
; #pragma unroll
;         for (int ai = 0; ai < 2; ++ai)
; #pragma unroll
;             for (int m = 0; m < 4; ++m) { const int row = row0 + ai * HALF + m * 16; const float rs = rsqrtf(ep[ai * 4 + m] * (1.0f / 1024.0f) + EPS);
;                 u16* rowp = O + (size_t)row * ldc + col0;
; #pragma unroll
;                 for (int bj = 0; bj < 2; ++bj) { f32x4 v0 = acc[ai][bj][m][0] * rs, v1 = acc[ai][bj][m][1] * rs;
;                     if (ACT == 1) {
; #pragma unroll
;                         for (int j = 0; j < 4; ++j) { const float a0 = fmaxf(v0[j], 0.f), a1 = fmaxf(v1[j], 0.f); v0[j] = a0 * a0; v1[j] = a1 * a1; } }
;                     u32x4 w; w.x = pk2(v0[0], v0[1]); w.y = pk2(v0[2], v0[3]); w.z = pk2(v1[0], v1[1]); w.w = pk2(v1[2], v1[3]);
;                     *(u32x4*)(rowp + bj * HALF) = w; } }
; template <class Epi>
; __device__ __forceinline__ void gemm_phase(LAS unsigned char* lds, const Gemm g, const StaticOrder& S, const Epi& E) {
;     ...
;             PG8_BAR; PG8_WAIT_L(0); PG8_MMA(1, 0, At, B0); PG8_BAR; PG8_SCHED;
;             PG8_STAGE(PG8_SB(1, 1), b3 + hstepB, voffB);
;             PG8_WAIT_V(6); PG8_BAR; PG8_MMA(1, 1, At, B1); PG8_BAR;
;         }
;         E(acc, cur, wr, wc, fr, fq, epre);
;         if (!has_next) break;
	s_waitcnt lgkmcnt(0)
	s_setprio 1
	s_waitcnt lgkmcnt(0)
	v_mfma_f32_16x16x32_bf16 v[60:63], v[146:149], v[166:169], v[60:63]
	v_mfma_f32_16x16x32_bf16 v[56:59], v[158:161], v[166:169], v[56:59]
	v_mfma_f32_16x16x32_bf16 v[48:51], v[146:149], v[182:185], v[48:51]
	v_mfma_f32_16x16x32_bf16 v[40:43], v[158:161], v[182:185], v[40:43]
	v_mfma_f32_16x16x32_bf16 v[32:35], v[146:149], v[190:193], v[32:35]
	v_mfma_f32_16x16x32_bf16 v[24:27], v[158:161], v[190:193], v[24:27]
	v_mfma_f32_16x16x32_bf16 v[16:19], v[146:149], v[198:201], v[16:19]
	v_mfma_f32_16x16x32_bf16 v[8:11], v[158:161], v[198:201], v[8:11]
	v_mfma_f32_16x16x32_bf16 v[60:63], v[154:157], v[178:181], v[60:63]
	v_mfma_f32_16x16x32_bf16 v[56:59], v[162:165], v[178:181], v[56:59]
	v_mfma_f32_16x16x32_bf16 v[48:51], v[154:157], v[186:189], v[48:51]
	v_mfma_f32_16x16x32_bf16 v[40:43], v[162:165], v[186:189], v[40:43]
	v_mfma_f32_16x16x32_bf16 v[32:35], v[154:157], v[194:197], v[32:35]
	v_mfma_f32_16x16x32_bf16 v[24:27], v[162:165], v[194:197], v[24:27]
	v_mfma_f32_16x16x32_bf16 v[16:19], v[154:157], v[202:205], v[16:19]
	v_mfma_f32_16x16x32_bf16 v[8:11], v[162:165], v[202:205], v[8:11]
	s_setprio 0
	s_barrier
	s_add_u32 s22, s22, 0x40080
	s_addc_u32 s23, s23, 0
	s_add_i32 s24, s24, s27
	v_lshl_add_u64 v[146:147], s[22:23], 0, v[132:133]
	s_mov_b32 m0, s24
	s_nop 0
	global_load_lds_dwordx4 v[146:147], off
	v_lshl_add_u64 v[146:147], s[22:23], 0, v[128:129]
	s_add_i32 m0, s24, 0x2000
	s_nop 0
	global_load_lds_dwordx4 v[146:147], off
	s_waitcnt vmcnt(6)
	s_barrier
	s_setprio 1
	v_mfma_f32_16x16x32_bf16 v[52:55], v[206:209], v[166:169], v[52:55]
	v_mfma_f32_16x16x32_bf16 v[44:47], v[214:217], v[166:169], v[44:47]
	v_mfma_f32_16x16x32_bf16 v[36:39], v[206:209], v[182:185], v[36:39]
	v_mfma_f32_16x16x32_bf16 v[28:31], v[214:217], v[182:185], v[28:31]
	v_mfma_f32_16x16x32_bf16 v[20:23], v[206:209], v[190:193], v[20:23]
	v_mfma_f32_16x16x32_bf16 v[12:15], v[214:217], v[190:193], v[12:15]
	v_mfma_f32_16x16x32_bf16 v[4:7], v[206:209], v[198:201], v[4:7]
	v_mfma_f32_16x16x32_bf16 v[0:3], v[214:217], v[198:201], v[0:3]
	v_mfma_f32_16x16x32_bf16 v[52:55], v[210:213], v[178:181], v[52:55]
	v_mfma_f32_16x16x32_bf16 v[44:47], v[218:221], v[178:181], v[44:47]
	v_mfma_f32_16x16x32_bf16 v[36:39], v[210:213], v[186:189], v[36:39]
	v_mfma_f32_16x16x32_bf16 v[28:31], v[218:221], v[186:189], v[28:31]
	v_mfma_f32_16x16x32_bf16 v[20:23], v[210:213], v[194:197], v[20:23]
	v_mfma_f32_16x16x32_bf16 v[12:15], v[218:221], v[194:197], v[12:15]
	v_mfma_f32_16x16x32_bf16 v[4:7], v[210:213], v[202:205], v[4:7]
	v_mfma_f32_16x16x32_bf16 v[0:3], v[218:221], v[202:205], v[0:3]
	s_setprio 0
	s_add_i32 s47, s47, 2
	s_add_u32 s20, s20, 0x100
	s_addc_u32 s21, s21, 0
	s_add_u32 s45, s45, 0x100
	s_addc_u32 s46, s46, 0
	s_cmp_gt_u32 s47, 13
	s_barrier
	s_cbranch_scc0 .LBB0_922
	s_mov_b64 s[24:25], 0x28000
	s_mov_b64 s[44:45], 0xc8000
	s_bfe_u32 vcc_lo, s18, 0x20003
	s_lshl_b32 vcc_lo, vcc_lo, 10
	s_add_i32 vcc_lo, vcc_lo, 0x20010
	v_lshl_add_u32 v236, v170, 2, vcc_lo
	ds_read_b32 v228, v236
	ds_read_b32 v229, v236 offset:64
	ds_read_b32 v230, v236 offset:128
	ds_read_b32 v231, v236 offset:192
	ds_read_b32 v232, v236 offset:512
	ds_read_b32 v233, v236 offset:576
	ds_read_b32 v234, v236 offset:640
	ds_read_b32 v235, v236 offset:704
	s_waitcnt lgkmcnt(0)
	v_lshl_add_u32 v154, s18, 8, v170
	v_lshl_or_b32 v208, s42, 8, v172
	v_mov_b64_e32 v[148:149], s[96:97]
	v_ashrrev_i32_e32 v209, 31, v208
	v_mad_i64_i32 v[210:211], s[20:21], v154, s40, v[148:149]
	v_lshlrev_b64 v[154:155], 1, v[208:209]
	v_lshl_add_u64 v[208:209], v[210:211], 0, v[154:155]
	s_mov_b32 s42, s10
	s_mov_b32 s18, s12
	s_mov_b64 s[22:23], s[16:17]
	v_mov_b32_e32 v178, v228
	v_pk_mul_f32 v[126:127], v[126:127], v[178:179] op_sel_hi:[1,0]
	v_pk_mul_f32 v[124:125], v[124:125], v[178:179] op_sel_hi:[1,0]
	v_pk_mul_f32 v[190:191], v[122:123], v[178:179] op_sel_hi:[1,0]
	v_pk_mul_f32 v[122:123], v[120:121], v[178:179] op_sel_hi:[1,0]
	v_cvt_pk_bf16_f32 v120, v124, v125
	v_cvt_pk_bf16_f32 v121, v126, v127
	v_cvt_pk_bf16_f32 v122, v122, v123
	v_cvt_pk_bf16_f32 v123, v190, v191
	v_pk_mul_f32 v[116:117], v[116:117], v[178:179] op_sel_hi:[1,0]
	global_store_dwordx4 v[208:209], v[120:123], off
	s_nop 0
	v_pk_mul_f32 v[118:119], v[118:119], v[178:179] op_sel_hi:[1,0]
	v_pk_mul_f32 v[120:121], v[110:111], v[178:179] op_sel_hi:[1,0]
	v_pk_mul_f32 v[110:111], v[108:109], v[178:179] op_sel_hi:[1,0]
	v_cvt_pk_bf16_f32 v108, v116, v117
	v_cvt_pk_bf16_f32 v109, v118, v119
	v_cvt_pk_bf16_f32 v110, v110, v111
	v_cvt_pk_bf16_f32 v111, v120, v121
	global_store_dwordx4 v[208:209], v[108:111], off offset:256
	s_nop 1
	v_mov_b32_e32 v108, v229
	v_pk_mul_f32 v[114:115], v[114:115], v[108:109] op_sel_hi:[1,0]
	v_pk_mul_f32 v[112:113], v[112:113], v[108:109] op_sel_hi:[1,0]
	v_pk_mul_f32 v[116:117], v[106:107], v[108:109] op_sel_hi:[1,0]
	v_pk_mul_f32 v[106:107], v[104:105], v[108:109] op_sel_hi:[1,0]
	v_lshl_add_u64 v[110:111], v[208:209], 0, s[24:25]
	v_cvt_pk_bf16_f32 v104, v112, v113
	v_cvt_pk_bf16_f32 v105, v114, v115
	v_cvt_pk_bf16_f32 v106, v106, v107
	v_cvt_pk_bf16_f32 v107, v116, v117
	global_store_dwordx4 v[110:111], v[104:107], off
	v_pk_mul_f32 v[100:101], v[100:101], v[108:109] op_sel_hi:[1,0]
	v_pk_mul_f32 v[112:113], v[98:99], v[108:109] op_sel_hi:[1,0]
	v_pk_mul_f32 v[98:99], v[96:97], v[108:109] op_sel_hi:[1,0]
	v_cvt_pk_bf16_f32 v96, v100, v101
	v_pk_mul_f32 v[102:103], v[102:103], v[108:109] op_sel_hi:[1,0]
	v_cvt_pk_bf16_f32 v98, v98, v99
	v_cvt_pk_bf16_f32 v97, v102, v103
	v_cvt_pk_bf16_f32 v99, v112, v113
	global_store_dwordx4 v[110:111], v[96:99], off offset:256
	s_nop 1
; __device__ __forceinline__ unsigned pk2(float lo, float hi) { const f32x2 v = (f32x2){lo, hi}; const bf16x2_t b = __builtin_convertvector(v, bf16x2_t); return __builtin_bit_cast(unsigned, b); }
;     __device__ __forceinline__ void operator()(const f32x4 (&acc)[2][2][4][2], const Unit& u, int wr, int wc, int fr, int fq, const float (&)[8]) const {
;     ...
;             for (int m = 0; m < 4; ++m) { const int row = row0 + ai * HALF + m * 16; const float rs = rsqrtf(ep[ai * 4 + m] * (1.0f / 1024.0f) + EPS);
;                 u16* rowp = O + (size_t)row * ldc + col0;
; #pragma unroll
;                 for (int bj = 0; bj < 2; ++bj) { f32x4 v0 = acc[ai][bj][m][0] * rs, v1 = acc[ai][bj][m][1] * rs;
;                     if (ACT == 1) {
; #pragma unroll
;                         for (int j = 0; j < 4; ++j) { const float a0 = fmaxf(v0[j], 0.f), a1 = fmaxf(v1[j], 0.f); v0[j] = a0 * a0; v1[j] = a1 * a1; } }
;                     u32x4 w; w.x = pk2(v0[0], v0[1]); w.y = pk2(v0[2], v0[3]); w.z = pk2(v1[0], v1[1]); w.w = pk2(v1[2], v1[3]);
;                     *(u32x4*)(rowp + bj * HALF) = w; } }
; template <class Epi>
; __device__ __forceinline__ void gemm_phase(LAS unsigned char* lds, const Gemm g, const StaticOrder& S, const Epi& E) {
;     ...
;         E(acc, cur, wr, wc, fr, fq, epre);
;         if (!has_next) break;
	v_lshl_add_u64 v[98:99], v[110:111], 0, s[24:25]
	v_mov_b32_e32 v100, v230
	v_pk_mul_f32 v[94:95], v[94:95], v[100:101] op_sel_hi:[1,0]
	v_pk_mul_f32 v[92:93], v[92:93], v[100:101] op_sel_hi:[1,0]
	v_pk_mul_f32 v[102:103], v[90:91], v[100:101] op_sel_hi:[1,0]
	v_pk_mul_f32 v[90:91], v[88:89], v[100:101] op_sel_hi:[1,0]
	v_cvt_pk_bf16_f32 v88, v92, v93
	v_cvt_pk_bf16_f32 v89, v94, v95
	v_cvt_pk_bf16_f32 v90, v90, v91
	v_cvt_pk_bf16_f32 v91, v102, v103
	v_pk_mul_f32 v[84:85], v[84:85], v[100:101] op_sel_hi:[1,0]
	global_store_dwordx4 v[98:99], v[88:91], off
	s_nop 0
	v_pk_mul_f32 v[86:87], v[86:87], v[100:101] op_sel_hi:[1,0]
	v_pk_mul_f32 v[88:89], v[78:79], v[100:101] op_sel_hi:[1,0]
	v_pk_mul_f32 v[78:79], v[76:77], v[100:101] op_sel_hi:[1,0]
	v_cvt_pk_bf16_f32 v76, v84, v85
	v_cvt_pk_bf16_f32 v77, v86, v87
	v_cvt_pk_bf16_f32 v78, v78, v79
	v_cvt_pk_bf16_f32 v79, v88, v89
	global_store_dwordx4 v[98:99], v[76:79], off offset:256
	s_nop 1
	v_mov_b32_e32 v76, v231
	v_pk_mul_f32 v[82:83], v[82:83], v[76:77] op_sel_hi:[1,0]
	v_pk_mul_f32 v[80:81], v[80:81], v[76:77] op_sel_hi:[1,0]
	v_pk_mul_f32 v[84:85], v[74:75], v[76:77] op_sel_hi:[1,0]
	v_pk_mul_f32 v[74:75], v[72:73], v[76:77] op_sel_hi:[1,0]
	v_lshl_add_u64 v[78:79], v[98:99], 0, s[24:25]
	v_cvt_pk_bf16_f32 v72, v80, v81
	v_cvt_pk_bf16_f32 v73, v82, v83
	v_cvt_pk_bf16_f32 v74, v74, v75
	v_cvt_pk_bf16_f32 v75, v84, v85
	global_store_dwordx4 v[78:79], v[72:75], off
	v_pk_mul_f32 v[68:69], v[68:69], v[76:77] op_sel_hi:[1,0]
	v_pk_mul_f32 v[80:81], v[66:67], v[76:77] op_sel_hi:[1,0]
	v_pk_mul_f32 v[66:67], v[64:65], v[76:77] op_sel_hi:[1,0]
	v_cvt_pk_bf16_f32 v64, v68, v69
	v_pk_mul_f32 v[70:71], v[70:71], v[76:77] op_sel_hi:[1,0]
	v_cvt_pk_bf16_f32 v66, v66, v67
	v_cvt_pk_bf16_f32 v65, v70, v71
	v_cvt_pk_bf16_f32 v67, v80, v81
	global_store_dwordx4 v[78:79], v[64:67], off offset:256
	s_nop 1
	v_lshl_add_u64 v[66:67], v[78:79], 0, s[44:45]
	v_mov_b32_e32 v68, v232
	v_pk_mul_f32 v[62:63], v[62:63], v[68:69] op_sel_hi:[1,0]
	v_pk_mul_f32 v[60:61], v[60:61], v[68:69] op_sel_hi:[1,0]
	v_pk_mul_f32 v[70:71], v[58:59], v[68:69] op_sel_hi:[1,0]
	v_pk_mul_f32 v[58:59], v[56:57], v[68:69] op_sel_hi:[1,0]
	v_cvt_pk_bf16_f32 v56, v60, v61
	v_cvt_pk_bf16_f32 v57, v62, v63
	v_cvt_pk_bf16_f32 v58, v58, v59
	v_cvt_pk_bf16_f32 v59, v70, v71
	v_pk_mul_f32 v[52:53], v[52:53], v[68:69] op_sel_hi:[1,0]
	global_store_dwordx4 v[66:67], v[56:59], off
	s_nop 0
	v_pk_mul_f32 v[54:55], v[54:55], v[68:69] op_sel_hi:[1,0]
	v_pk_mul_f32 v[56:57], v[46:47], v[68:69] op_sel_hi:[1,0]
	v_pk_mul_f32 v[46:47], v[44:45], v[68:69] op_sel_hi:[1,0]
	v_cvt_pk_bf16_f32 v44, v52, v53
	v_cvt_pk_bf16_f32 v45, v54, v55
	v_cvt_pk_bf16_f32 v46, v46, v47
	v_cvt_pk_bf16_f32 v47, v56, v57
	global_store_dwordx4 v[66:67], v[44:47], off offset:256
	s_nop 1
	v_mov_b32_e32 v44, v233
	v_pk_mul_f32 v[50:51], v[50:51], v[44:45] op_sel_hi:[1,0]
	v_pk_mul_f32 v[48:49], v[48:49], v[44:45] op_sel_hi:[1,0]
	v_pk_mul_f32 v[52:53], v[42:43], v[44:45] op_sel_hi:[1,0]
	v_pk_mul_f32 v[42:43], v[40:41], v[44:45] op_sel_hi:[1,0]
	v_lshl_add_u64 v[46:47], v[66:67], 0, s[24:25]
	v_cvt_pk_bf16_f32 v40, v48, v49
	v_cvt_pk_bf16_f32 v41, v50, v51
	v_cvt_pk_bf16_f32 v42, v42, v43
	v_cvt_pk_bf16_f32 v43, v52, v53
	global_store_dwordx4 v[46:47], v[40:43], off
	v_pk_mul_f32 v[36:37], v[36:37], v[44:45] op_sel_hi:[1,0]
	v_pk_mul_f32 v[48:49], v[30:31], v[44:45] op_sel_hi:[1,0]
	v_pk_mul_f32 v[30:31], v[28:29], v[44:45] op_sel_hi:[1,0]
	v_cvt_pk_bf16_f32 v28, v36, v37
	v_pk_mul_f32 v[38:39], v[38:39], v[44:45] op_sel_hi:[1,0]
	v_cvt_pk_bf16_f32 v30, v30, v31
	v_cvt_pk_bf16_f32 v29, v38, v39
	v_cvt_pk_bf16_f32 v31, v48, v49
	global_store_dwordx4 v[46:47], v[28:31], off offset:256
	s_nop 1
	v_lshl_add_u64 v[30:31], v[46:47], 0, s[24:25]
	v_mov_b32_e32 v36, v234
	v_pk_mul_f32 v[34:35], v[34:35], v[36:37] op_sel_hi:[1,0]
	v_pk_mul_f32 v[32:33], v[32:33], v[36:37] op_sel_hi:[1,0]
	v_pk_mul_f32 v[38:39], v[26:27], v[36:37] op_sel_hi:[1,0]
	v_pk_mul_f32 v[26:27], v[24:25], v[36:37] op_sel_hi:[1,0]
	v_cvt_pk_bf16_f32 v24, v32, v33
	v_cvt_pk_bf16_f32 v25, v34, v35
	v_cvt_pk_bf16_f32 v26, v26, v27
	v_cvt_pk_bf16_f32 v27, v38, v39
	v_pk_mul_f32 v[20:21], v[20:21], v[36:37] op_sel_hi:[1,0]
	global_store_dwordx4 v[30:31], v[24:27], off
	s_nop 0
	v_pk_mul_f32 v[22:23], v[22:23], v[36:37] op_sel_hi:[1,0]
	v_pk_mul_f32 v[24:25], v[14:15], v[36:37] op_sel_hi:[1,0]
	v_pk_mul_f32 v[14:15], v[12:13], v[36:37] op_sel_hi:[1,0]
	v_cvt_pk_bf16_f32 v12, v20, v21
	v_cvt_pk_bf16_f32 v13, v22, v23
	v_cvt_pk_bf16_f32 v14, v14, v15
	v_cvt_pk_bf16_f32 v15, v24, v25
	global_store_dwordx4 v[30:31], v[12:15], off offset:256
	s_nop 1
	v_mov_b32_e32 v12, v235
	v_pk_mul_f32 v[18:19], v[18:19], v[12:13] op_sel_hi:[1,0]
	v_pk_mul_f32 v[16:17], v[16:17], v[12:13] op_sel_hi:[1,0]
	v_pk_mul_f32 v[20:21], v[10:11], v[12:13] op_sel_hi:[1,0]
	v_pk_mul_f32 v[10:11], v[8:9], v[12:13] op_sel_hi:[1,0]
	v_lshl_add_u64 v[14:15], v[30:31], 0, s[24:25]
	v_cvt_pk_bf16_f32 v8, v16, v17
	v_cvt_pk_bf16_f32 v9, v18, v19
	v_cvt_pk_bf16_f32 v10, v10, v11
	v_cvt_pk_bf16_f32 v11, v20, v21
	global_store_dwordx4 v[14:15], v[8:11], off
	v_pk_mul_f32 v[6:7], v[6:7], v[12:13] op_sel_hi:[1,0]
	v_pk_mul_f32 v[4:5], v[4:5], v[12:13] op_sel_hi:[1,0]
	v_pk_mul_f32 v[8:9], v[2:3], v[12:13] op_sel_hi:[1,0]
	v_pk_mul_f32 v[2:3], v[0:1], v[12:13] op_sel_hi:[1,0]
	v_cvt_pk_bf16_f32 v0, v4, v5
	v_cvt_pk_bf16_f32 v1, v6, v7
	v_cvt_pk_bf16_f32 v2, v2, v3
	v_cvt_pk_bf16_f32 v3, v8, v9
	s_and_b64 vcc, exec, s[0:1]
	s_mov_b64 s[20:21], s[14:15]
	global_store_dwordx4 v[14:15], v[0:3], off offset:256
	s_cbranch_vccz .LBB0_919
	s_waitcnt vmcnt(0)
	v_readlane_b32 s40, v251, 54
	s_cmpk_gt_u32 s7, 0xff
	v_readlane_b32 s41, v251, 55
	s_cbranch_scc1 .LBB0_926
	s_barrier

; #define PG8_STAGE(bufoff, gbase, voff) do { _Pragma("unroll") for (int _i = 0; _i < 2; ++_i) \
;         __builtin_amdgcn_global_load_lds((const unsigned*)((const char*)(gbase) + (voff)[_i]), (LAS unsigned*)(lds + (bufoff) + ldsw + _i * 8192), 16, 0, 0); } while (0)
; #define PG8_LDA(dst, b, h) do { _Pragma("unroll") for (int m = 0; m < 4; ++m) _Pragma("unroll") for (int k = 0; k < 2; ++k) dst[m][k] = *(const LAS bf16x8*)(lds + PG8_SA(b, h) + aoff + m * 2048 + k * 1024); } while (0)
; #define PG8_LDB(dst, b, h) do { _Pragma("unroll") for (int n = 0; n < 2; ++n) _Pragma("unroll") for (int k = 0; k < 2; ++k) dst[n][k] = *(const LAS bf16x8*)(lds + PG8_SB(b, h) + boff + n * 2048 + k * 1024); } while (0)
; #define PG8_MMA(ai, bj, At, Bt) do { __builtin_amdgcn_s_setprio(1); _Pragma("unroll") for (int m = 0; m < 4; ++m) _Pragma("unroll") for (int n = 0; n < 2; ++n) _Pragma("unroll") for (int k = 0; k < 2; ++k) \
;         acc[ai][bj][m][n] = __builtin_amdgcn_mfma_f32_16x16x32_bf16(Bt[n][k], At[m][k], acc[ai][bj][m][n], 0, 0, 0); __builtin_amdgcn_s_setprio(0); } while (0)
; #define PG8_WAIT_V(n) asm volatile("s_waitcnt vmcnt(" #n ")" ::: "memory")
; #define PG8_WAIT_L(n) asm volatile("s_waitcnt lgkmcnt(" #n ")" ::: "memory")
; #define PG8_BAR __builtin_amdgcn_s_barrier()
; #define PG8_SCHED __builtin_amdgcn_sched_barrier(0)
; template <class Epi>
; __device__ __forceinline__ void gemm_phase(LAS unsigned char* lds, const Gemm g, const StaticOrder& S, const Epi& E) {
;     ...
;             PG8_LDB(B0, 0, 0); PG8_SCHED; PG8_LDA(At, 0, 0); PG8_STAGE(PG8_SA(1, 1), a1 + hstepA, voffA);
;             PG8_WAIT_L(8); PG8_BAR; PG8_WAIT_L(0); PG8_MMA(0, 0, At, B0); PG8_BAR; PG8_SCHED;
;             PG8_LDB(B1, 0, 1); PG8_STAGE(PG8_SB(0, 0), b2, voffB);
;             PG8_BAR; PG8_WAIT_L(0); PG8_MMA(0, 1, At, B1); PG8_BAR;
;             PG8_LDA(At, 0, 1); PG8_STAGE(PG8_SA(0, 0), a2, voffA);
;             PG8_BAR; PG8_WAIT_L(0); PG8_MMA(1, 0, At, B0); PG8_BAR; PG8_SCHED;
;             PG8_STAGE(PG8_SB(0, 1), b2 + hstepB, voffB);
;             PG8_WAIT_V(6); PG8_BAR; PG8_MMA(1, 1, At, B1); PG8_BAR;
.LBB0_1204:
	ds_read_b128 v[146:149], v176
	ds_read_b128 v[154:157], v176 offset:1024
	ds_read_b128 v[158:161], v176 offset:2048
	ds_read_b128 v[162:165], v176 offset:3072
	s_add_u32 s22, s20, 0xfffc0080
	s_addc_u32 s23, s21, -1
	s_cmp_eq_u32 s45, 12
	s_cselect_b32 s25, s13, s23
	s_cselect_b32 s24, s41, s22
	s_cselect_b32 s23, s11, s44
	s_cselect_b32 s22, s42, s43
	v_lshl_add_u64 v[150:151], s[20:21], 0, v[138:139]
	s_add_i32 m0, s19, 0xc000
	ds_read_b128 v[166:169], v177
	ds_read_b128 v[170:173], v177 offset:1024
	ds_read_b128 v[180:183], v177 offset:2048
	ds_read_b128 v[184:187], v177 offset:3072
	ds_read_b128 v[188:191], v177 offset:4096
	ds_read_b128 v[192:195], v177 offset:5120
	ds_read_b128 v[196:199], v177 offset:6144
	ds_read_b128 v[200:203], v177 offset:7168
	global_load_lds_dwordx4 v[150:151], off
	v_lshl_add_u64 v[150:151], s[20:21], 0, v[140:141]
	s_add_i32 m0, s19, 0xe000
	s_nop 0
	global_load_lds_dwordx4 v[150:151], off
	s_waitcnt lgkmcnt(8)
	s_barrier
	s_waitcnt lgkmcnt(0)
	s_setprio 1
	s_waitcnt lgkmcnt(0)
	v_mfma_f32_16x16x32_bf16 v[124:127], v[146:149], v[166:169], v[124:127]
	v_mfma_f32_16x16x32_bf16 v[120:123], v[158:161], v[166:169], v[120:123]
	v_mfma_f32_16x16x32_bf16 v[108:111], v[146:149], v[180:183], v[108:111]
	v_mfma_f32_16x16x32_bf16 v[104:107], v[158:161], v[180:183], v[104:107]
	v_mfma_f32_16x16x32_bf16 v[92:95], v[146:149], v[188:191], v[92:95]
	v_mfma_f32_16x16x32_bf16 v[88:91], v[158:161], v[188:191], v[88:91]
	v_mfma_f32_16x16x32_bf16 v[76:79], v[146:149], v[196:199], v[76:79]
	v_mfma_f32_16x16x32_bf16 v[72:75], v[158:161], v[196:199], v[72:75]
	v_mfma_f32_16x16x32_bf16 v[124:127], v[154:157], v[170:173], v[124:127]
	v_mfma_f32_16x16x32_bf16 v[120:123], v[162:165], v[170:173], v[120:123]
	v_mfma_f32_16x16x32_bf16 v[108:111], v[154:157], v[184:187], v[108:111]
	v_mfma_f32_16x16x32_bf16 v[104:107], v[162:165], v[184:187], v[104:107]
	v_mfma_f32_16x16x32_bf16 v[92:95], v[154:157], v[192:195], v[92:95]
	v_mfma_f32_16x16x32_bf16 v[88:91], v[162:165], v[192:195], v[88:91]
	v_mfma_f32_16x16x32_bf16 v[76:79], v[154:157], v[200:203], v[76:79]
	v_mfma_f32_16x16x32_bf16 v[72:75], v[162:165], v[200:203], v[72:75]
	s_setprio 0
	s_barrier
	s_add_i32 s46, s37, s28
	v_lshl_add_u64 v[150:151], s[22:23], 0, v[130:131]
	s_mov_b32 m0, s46
	ds_read_b128 v[204:207], v178
	ds_read_b128 v[208:211], v178 offset:1024
	ds_read_b128 v[212:215], v178 offset:2048
	ds_read_b128 v[216:219], v178 offset:3072
	global_load_lds_dwordx4 v[150:151], off
	v_lshl_add_u64 v[220:221], s[22:23], 0, v[134:135]
	s_add_i32 m0, s46, 0x2000
	s_nop 0
	global_load_lds_dwordx4 v[220:221], off
	s_barrier
	s_waitcnt lgkmcnt(0)
	s_setprio 1
	s_waitcnt lgkmcnt(0)
	v_mfma_f32_16x16x32_bf16 v[116:119], v[204:207], v[166:169], v[116:119]
	v_mfma_f32_16x16x32_bf16 v[112:115], v[212:215], v[166:169], v[112:115]
	v_mfma_f32_16x16x32_bf16 v[100:103], v[204:207], v[180:183], v[100:103]
	v_mfma_f32_16x16x32_bf16 v[96:99], v[212:215], v[180:183], v[96:99]
	v_mfma_f32_16x16x32_bf16 v[84:87], v[204:207], v[188:191], v[84:87]
	v_mfma_f32_16x16x32_bf16 v[80:83], v[212:215], v[188:191], v[80:83]
	v_mfma_f32_16x16x32_bf16 v[68:71], v[204:207], v[196:199], v[68:71]
	v_mfma_f32_16x16x32_bf16 v[64:67], v[212:215], v[196:199], v[64:67]
	v_mfma_f32_16x16x32_bf16 v[116:119], v[208:211], v[170:173], v[116:119]
	v_mfma_f32_16x16x32_bf16 v[112:115], v[216:219], v[170:173], v[112:115]
	v_mfma_f32_16x16x32_bf16 v[100:103], v[208:211], v[184:187], v[100:103]
	v_mfma_f32_16x16x32_bf16 v[96:99], v[216:219], v[184:187], v[96:99]
	v_mfma_f32_16x16x32_bf16 v[84:87], v[208:211], v[192:195], v[84:87]
	v_mfma_f32_16x16x32_bf16 v[80:83], v[216:219], v[192:195], v[80:83]
	v_mfma_f32_16x16x32_bf16 v[68:71], v[208:211], v[200:203], v[68:71]
	v_mfma_f32_16x16x32_bf16 v[64:67], v[216:219], v[200:203], v[64:67]
	s_setprio 0
	s_mov_b32 m0, s19
	v_lshl_add_u64 v[222:223], s[24:25], 0, v[128:129]
	s_barrier
	ds_read_b128 v[166:169], v177 offset:16384
	ds_read_b128 v[170:173], v177 offset:17408
	ds_read_b128 v[180:183], v177 offset:18432
	ds_read_b128 v[184:187], v177 offset:19456
	ds_read_b128 v[188:191], v177 offset:20480
	ds_read_b128 v[192:195], v177 offset:21504
	ds_read_b128 v[196:199], v177 offset:22528
	ds_read_b128 v[200:203], v177 offset:23552
	global_load_lds_dwordx4 v[222:223], off
	v_lshl_add_u64 v[224:225], s[24:25], 0, v[132:133]
	s_mov_b32 m0, s29
	s_nop 0
	global_load_lds_dwordx4 v[224:225], off
	s_barrier
	s_waitcnt lgkmcnt(0)
	s_setprio 1
	s_waitcnt lgkmcnt(0)
	v_mfma_f32_16x16x32_bf16 v[60:63], v[146:149], v[166:169], v[60:63]
	v_mfma_f32_16x16x32_bf16 v[56:59], v[158:161], v[166:169], v[56:59]
	v_mfma_f32_16x16x32_bf16 v[44:47], v[146:149], v[180:183], v[44:47]
	v_mfma_f32_16x16x32_bf16 v[40:43], v[158:161], v[180:183], v[40:43]
	v_mfma_f32_16x16x32_bf16 v[28:31], v[146:149], v[188:191], v[28:31]
	v_mfma_f32_16x16x32_bf16 v[24:27], v[158:161], v[188:191], v[24:27]
	v_mfma_f32_16x16x32_bf16 v[12:15], v[146:149], v[196:199], v[12:15]
	v_mfma_f32_16x16x32_bf16 v[8:11], v[158:161], v[196:199], v[8:11]
	v_mfma_f32_16x16x32_bf16 v[60:63], v[154:157], v[170:173], v[60:63]
	v_mfma_f32_16x16x32_bf16 v[56:59], v[162:165], v[170:173], v[56:59]
	v_mfma_f32_16x16x32_bf16 v[44:47], v[154:157], v[184:187], v[44:47]
	v_mfma_f32_16x16x32_bf16 v[40:43], v[162:165], v[184:187], v[40:43]
	v_mfma_f32_16x16x32_bf16 v[28:31], v[154:157], v[192:195], v[28:31]
	v_mfma_f32_16x16x32_bf16 v[24:27], v[162:165], v[192:195], v[24:27]
	v_mfma_f32_16x16x32_bf16 v[12:15], v[154:157], v[200:203], v[12:15]
	v_mfma_f32_16x16x32_bf16 v[8:11], v[162:165], v[200:203], v[8:11]
	s_setprio 0
	s_barrier
; #define PG8_STAGE(bufoff, gbase, voff) do { _Pragma("unroll") for (int _i = 0; _i < 2; ++_i) \
;         __builtin_amdgcn_global_load_lds((const unsigned*)((const char*)(gbase) + (voff)[_i]), (LAS unsigned*)(lds + (bufoff) + ldsw + _i * 8192), 16, 0, 0); } while (0)
; #define PG8_LDA(dst, b, h) do { _Pragma("unroll") for (int m = 0; m < 4; ++m) _Pragma("unroll") for (int k = 0; k < 2; ++k) dst[m][k] = *(const LAS bf16x8*)(lds + PG8_SA(b, h) + aoff + m * 2048 + k * 1024); } while (0)
; #define PG8_LDB(dst, b, h) do { _Pragma("unroll") for (int n = 0; n < 2; ++n) _Pragma("unroll") for (int k = 0; k < 2; ++k) dst[n][k] = *(const LAS bf16x8*)(lds + PG8_SB(b, h) + boff + n * 2048 + k * 1024); } while (0)
; #define PG8_MMA(ai, bj, At, Bt) do { __builtin_amdgcn_s_setprio(1); _Pragma("unroll") for (int m = 0; m < 4; ++m) _Pragma("unroll") for (int n = 0; n < 2; ++n) _Pragma("unroll") for (int k = 0; k < 2; ++k) \
;         acc[ai][bj][m][n] = __builtin_amdgcn_mfma_f32_16x16x32_bf16(Bt[n][k], At[m][k], acc[ai][bj][m][n], 0, 0, 0); __builtin_amdgcn_s_setprio(0); } while (0)
; #define PG8_WAIT_V(n) asm volatile("s_waitcnt vmcnt(" #n ")" ::: "memory")
; #define PG8_WAIT_L(n) asm volatile("s_waitcnt lgkmcnt(" #n ")" ::: "memory")
; #define PG8_BAR __builtin_amdgcn_s_barrier()
; #define PG8_SCHED __builtin_amdgcn_sched_barrier(0)
; template <class Epi>
; __device__ __forceinline__ void gemm_phase(LAS unsigned char* lds, const Gemm g, const StaticOrder& S, const Epi& E) {
;     ...
;             PG8_WAIT_V(6); PG8_BAR; PG8_MMA(1, 1, At, B1); PG8_BAR;
;             PG8_LDB(B0, 1, 0); PG8_SCHED; PG8_LDA(At, 1, 0); PG8_STAGE(PG8_SA(0, 1), a2 + hstepA, voffA);
;             PG8_WAIT_L(8); PG8_BAR; PG8_WAIT_L(0); PG8_MMA(0, 0, At, B0); PG8_BAR; PG8_SCHED;
;             PG8_LDB(B1, 1, 1); PG8_STAGE(PG8_SB(1, 0), b3, voffB);
;             PG8_BAR; PG8_WAIT_L(0); PG8_MMA(0, 1, At, B1); PG8_BAR;
;             PG8_LDA(At, 1, 1); PG8_STAGE(PG8_SA(1, 0), a3, voffA);
;             PG8_BAR; PG8_WAIT_L(0); PG8_MMA(1, 0, At, B0); PG8_BAR; PG8_SCHED;
	s_add_u32 s46, s22, 0x40000
	s_addc_u32 s47, s23, 0
	s_add_i32 s48, s38, s28
	v_lshl_add_u64 v[146:147], s[46:47], 0, v[130:131]
	s_mov_b32 m0, s48
	s_nop 0
	global_load_lds_dwordx4 v[146:147], off
	v_lshl_add_u64 v[146:147], s[46:47], 0, v[134:135]
	s_add_i32 m0, s48, 0x2000
	s_nop 0
	global_load_lds_dwordx4 v[146:147], off
	s_waitcnt vmcnt(6)
	s_barrier
	s_setprio 1
	v_mfma_f32_16x16x32_bf16 v[52:55], v[204:207], v[166:169], v[52:55]
	v_mfma_f32_16x16x32_bf16 v[48:51], v[212:215], v[166:169], v[48:51]
	v_mfma_f32_16x16x32_bf16 v[36:39], v[204:207], v[180:183], v[36:39]
	v_mfma_f32_16x16x32_bf16 v[32:35], v[212:215], v[180:183], v[32:35]
	v_mfma_f32_16x16x32_bf16 v[20:23], v[204:207], v[188:191], v[20:23]
	v_mfma_f32_16x16x32_bf16 v[16:19], v[212:215], v[188:191], v[16:19]
	v_mfma_f32_16x16x32_bf16 v[4:7], v[204:207], v[196:199], v[4:7]
	v_mfma_f32_16x16x32_bf16 v[0:3], v[212:215], v[196:199], v[0:3]
	v_mfma_f32_16x16x32_bf16 v[52:55], v[208:211], v[170:173], v[52:55]
	v_mfma_f32_16x16x32_bf16 v[48:51], v[216:219], v[170:173], v[48:51]
	v_mfma_f32_16x16x32_bf16 v[36:39], v[208:211], v[184:187], v[36:39]
	v_mfma_f32_16x16x32_bf16 v[32:35], v[216:219], v[184:187], v[32:35]
	v_mfma_f32_16x16x32_bf16 v[20:23], v[208:211], v[192:195], v[20:23]
	v_mfma_f32_16x16x32_bf16 v[16:19], v[216:219], v[192:195], v[16:19]
	v_mfma_f32_16x16x32_bf16 v[4:7], v[208:211], v[200:203], v[4:7]
	v_mfma_f32_16x16x32_bf16 v[0:3], v[216:219], v[200:203], v[0:3]
	s_setprio 0
	s_add_i32 s46, 0, 0x18000
	v_add_u32_e32 v162, s46, v174
	s_barrier
	ds_read_b128 v[146:149], v162
	ds_read_b128 v[154:157], v162 offset:1024
	ds_read_b128 v[158:161], v162 offset:2048
	ds_read_b128 v[162:165], v162 offset:3072
	s_add_u32 s24, s24, 0x40000
	s_addc_u32 s25, s25, 0
	s_mov_b32 m0, s30
	v_lshl_add_u64 v[204:205], s[24:25], 0, v[128:129]
	ds_read_b128 v[166:169], v177 offset:32768
	ds_read_b128 v[170:173], v177 offset:33792
	ds_read_b128 v[180:183], v177 offset:34816
	ds_read_b128 v[184:187], v177 offset:35840
	ds_read_b128 v[188:191], v177 offset:36864
	ds_read_b128 v[192:195], v177 offset:37888
	ds_read_b128 v[196:199], v177 offset:38912
	ds_read_b128 v[200:203], v177 offset:39936
	global_load_lds_dwordx4 v[204:205], off
	v_lshl_add_u64 v[204:205], s[24:25], 0, v[132:133]
	s_mov_b32 m0, s31
	s_nop 0
	global_load_lds_dwordx4 v[204:205], off
	s_waitcnt lgkmcnt(8)
	s_barrier
	s_waitcnt lgkmcnt(0)
	s_setprio 1
	s_waitcnt lgkmcnt(0)
	v_mfma_f32_16x16x32_bf16 v[124:127], v[146:149], v[166:169], v[124:127]
	v_mfma_f32_16x16x32_bf16 v[120:123], v[158:161], v[166:169], v[120:123]
	v_mfma_f32_16x16x32_bf16 v[108:111], v[146:149], v[180:183], v[108:111]
	v_mfma_f32_16x16x32_bf16 v[104:107], v[158:161], v[180:183], v[104:107]
	v_mfma_f32_16x16x32_bf16 v[92:95], v[146:149], v[188:191], v[92:95]
	v_mfma_f32_16x16x32_bf16 v[88:91], v[158:161], v[188:191], v[88:91]
	v_mfma_f32_16x16x32_bf16 v[76:79], v[146:149], v[196:199], v[76:79]
	v_mfma_f32_16x16x32_bf16 v[72:75], v[158:161], v[196:199], v[72:75]
	v_mfma_f32_16x16x32_bf16 v[124:127], v[154:157], v[170:173], v[124:127]
	v_mfma_f32_16x16x32_bf16 v[120:123], v[162:165], v[170:173], v[120:123]
	v_mfma_f32_16x16x32_bf16 v[108:111], v[154:157], v[184:187], v[108:111]
	v_mfma_f32_16x16x32_bf16 v[104:107], v[162:165], v[184:187], v[104:107]
	v_mfma_f32_16x16x32_bf16 v[92:95], v[154:157], v[192:195], v[92:95]
	v_mfma_f32_16x16x32_bf16 v[88:91], v[162:165], v[192:195], v[88:91]
	v_mfma_f32_16x16x32_bf16 v[76:79], v[154:157], v[200:203], v[76:79]
	v_mfma_f32_16x16x32_bf16 v[72:75], v[162:165], v[200:203], v[72:75]
	s_setprio 0
	s_barrier
	s_add_i32 s24, 0, 0x1c000
	s_add_i32 s25, s46, s28
	v_add_u32_e32 v216, s24, v174
	v_lshl_add_u64 v[150:151], v[150:151], 0, s[4:5]
	s_mov_b32 m0, s25
	ds_read_b128 v[204:207], v216
	ds_read_b128 v[208:211], v216 offset:1024
	ds_read_b128 v[212:215], v216 offset:2048
	ds_read_b128 v[216:219], v216 offset:3072
	global_load_lds_dwordx4 v[150:151], off
	v_lshl_add_u64 v[150:151], v[220:221], 0, s[4:5]
	s_add_i32 m0, s25, 0x2000
	s_nop 0
	global_load_lds_dwordx4 v[150:151], off
	s_barrier
	s_waitcnt lgkmcnt(0)
	s_setprio 1
	s_waitcnt lgkmcnt(0)
	v_mfma_f32_16x16x32_bf16 v[116:119], v[204:207], v[166:169], v[116:119]
	v_mfma_f32_16x16x32_bf16 v[112:115], v[212:215], v[166:169], v[112:115]
	v_mfma_f32_16x16x32_bf16 v[100:103], v[204:207], v[180:183], v[100:103]
	v_mfma_f32_16x16x32_bf16 v[96:99], v[212:215], v[180:183], v[96:99]
	v_mfma_f32_16x16x32_bf16 v[84:87], v[204:207], v[188:191], v[84:87]
	v_mfma_f32_16x16x32_bf16 v[80:83], v[212:215], v[188:191], v[80:83]
	v_mfma_f32_16x16x32_bf16 v[68:71], v[204:207], v[196:199], v[68:71]
	v_mfma_f32_16x16x32_bf16 v[64:67], v[212:215], v[196:199], v[64:67]
	v_mfma_f32_16x16x32_bf16 v[116:119], v[208:211], v[170:173], v[116:119]
	v_mfma_f32_16x16x32_bf16 v[112:115], v[216:219], v[170:173], v[112:115]
	v_mfma_f32_16x16x32_bf16 v[100:103], v[208:211], v[184:187], v[100:103]
	v_mfma_f32_16x16x32_bf16 v[96:99], v[216:219], v[184:187], v[96:99]
	v_mfma_f32_16x16x32_bf16 v[84:87], v[208:211], v[192:195], v[84:87]
	v_mfma_f32_16x16x32_bf16 v[80:83], v[216:219], v[192:195], v[80:83]
	v_mfma_f32_16x16x32_bf16 v[68:71], v[208:211], v[200:203], v[68:71]
	v_mfma_f32_16x16x32_bf16 v[64:67], v[216:219], v[200:203], v[64:67]
	s_setprio 0
	s_mov_b32 m0, s34
	v_lshl_add_u64 v[150:151], v[222:223], 0, s[4:5]
	s_barrier
	ds_read_b128 v[166:169], v177 offset:49152
	ds_read_b128 v[170:173], v177 offset:50176
	ds_read_b128 v[180:183], v177 offset:51200
	ds_read_b128 v[184:187], v177 offset:52224
	ds_read_b128 v[188:191], v177 offset:53248
	ds_read_b128 v[192:195], v177 offset:54272
	ds_read_b128 v[196:199], v177 offset:55296
	ds_read_b128 v[200:203], v177 offset:56320
	global_load_lds_dwordx4 v[150:151], off
	v_lshl_add_u64 v[150:151], v[224:225], 0, s[4:5]
	s_mov_b32 m0, s35
	s_nop 0
	global_load_lds_dwordx4 v[150:151], off
	s_barrier
; __device__ __forceinline__ unsigned pk2(float lo, float hi) { const f32x2 v = (f32x2){lo, hi}; const bf16x2_t b = __builtin_convertvector(v, bf16x2_t); return __builtin_bit_cast(unsigned, b); }
; #define PG8_STAGE(bufoff, gbase, voff) do { _Pragma("unroll") for (int _i = 0; _i < 2; ++_i) \
;         __builtin_amdgcn_global_load_lds((const unsigned*)((const char*)(gbase) + (voff)[_i]), (LAS unsigned*)(lds + (bufoff) + ldsw + _i * 8192), 16, 0, 0); } while (0)
; #define PG8_MMA(ai, bj, At, Bt) do { __builtin_amdgcn_s_setprio(1); _Pragma("unroll") for (int m = 0; m < 4; ++m) _Pragma("unroll") for (int n = 0; n < 2; ++n) _Pragma("unroll") for (int k = 0; k < 2; ++k) \
;         acc[ai][bj][m][n] = __builtin_amdgcn_mfma_f32_16x16x32_bf16(Bt[n][k], At[m][k], acc[ai][bj][m][n], 0, 0, 0); __builtin_amdgcn_s_setprio(0); } while (0)
; #define PG8_WAIT_V(n) asm volatile("s_waitcnt vmcnt(" #n ")" ::: "memory")
;     __device__ __forceinline__ void operator()(const f32x4 (&acc)[2][2][4][2], const Unit& u, int wr, int wc, int fr, int fq, const float (&)[8]) const {
;     ...
;         const int col0 = u.pn * BM + wc * 32 + 8 * fq;
; #pragma unroll
;         for (int ai = 0; ai < 2; ++ai)
; #pragma unroll
;             for (int m = 0; m < 4; ++m) { const int row = row0 + ai * HALF + m * 16; const float rs = rsqrtf(ep[ai * 4 + m] * (1.0f / 1024.0f) + EPS);
;                 u16* rowp = O + (size_t)row * ldc + col0;
; #pragma unroll
;                 for (int bj = 0; bj < 2; ++bj) { f32x4 v0 = acc[ai][bj][m][0] * rs, v1 = acc[ai][bj][m][1] * rs;
;                     if (ACT == 1) {
; #pragma unroll
;                         for (int j = 0; j < 4; ++j) { const float a0 = fmaxf(v0[j], 0.f), a1 = fmaxf(v1[j], 0.f); v0[j] = a0 * a0; v1[j] = a1 * a1; } }
;                     u32x4 w; w.x = pk2(v0[0], v0[1]); w.y = pk2(v0[2], v0[3]); w.z = pk2(v1[0], v1[1]); w.w = pk2(v1[2], v1[3]);
;                     *(u32x4*)(rowp + bj * HALF) = w; } }
; template <class Epi>
; __device__ __forceinline__ void gemm_phase(LAS unsigned char* lds, const Gemm g, const StaticOrder& S, const Epi& E) {
;     ...
;             PG8_BAR; PG8_WAIT_L(0); PG8_MMA(1, 0, At, B0); PG8_BAR; PG8_SCHED;
;             PG8_STAGE(PG8_SB(1, 1), b3 + hstepB, voffB);
;             PG8_WAIT_V(6); PG8_BAR; PG8_MMA(1, 1, At, B1); PG8_BAR;
;         }
;         E(acc, cur, wr, wc, fr, fq, epre);
;         if (!has_next) break;
	s_waitcnt lgkmcnt(0)
	s_setprio 1
	s_waitcnt lgkmcnt(0)
	v_mfma_f32_16x16x32_bf16 v[60:63], v[146:149], v[166:169], v[60:63]
	v_mfma_f32_16x16x32_bf16 v[56:59], v[158:161], v[166:169], v[56:59]
	v_mfma_f32_16x16x32_bf16 v[44:47], v[146:149], v[180:183], v[44:47]
	v_mfma_f32_16x16x32_bf16 v[40:43], v[158:161], v[180:183], v[40:43]
	v_mfma_f32_16x16x32_bf16 v[28:31], v[146:149], v[188:191], v[28:31]
	v_mfma_f32_16x16x32_bf16 v[24:27], v[158:161], v[188:191], v[24:27]
	v_mfma_f32_16x16x32_bf16 v[12:15], v[146:149], v[196:199], v[12:15]
	v_mfma_f32_16x16x32_bf16 v[8:11], v[158:161], v[196:199], v[8:11]
	v_mfma_f32_16x16x32_bf16 v[60:63], v[154:157], v[170:173], v[60:63]
	v_mfma_f32_16x16x32_bf16 v[56:59], v[162:165], v[170:173], v[56:59]
	v_mfma_f32_16x16x32_bf16 v[44:47], v[154:157], v[184:187], v[44:47]
	v_mfma_f32_16x16x32_bf16 v[40:43], v[162:165], v[184:187], v[40:43]
	v_mfma_f32_16x16x32_bf16 v[28:31], v[154:157], v[192:195], v[28:31]
	v_mfma_f32_16x16x32_bf16 v[24:27], v[162:165], v[192:195], v[24:27]
	v_mfma_f32_16x16x32_bf16 v[12:15], v[154:157], v[200:203], v[12:15]
	v_mfma_f32_16x16x32_bf16 v[8:11], v[162:165], v[200:203], v[8:11]
	s_setprio 0
	s_barrier
	s_add_u32 s22, s22, 0x40080
	s_addc_u32 s23, s23, 0
	s_add_i32 s24, s24, s28
	v_lshl_add_u64 v[146:147], s[22:23], 0, v[130:131]
	s_mov_b32 m0, s24
	s_nop 0
	global_load_lds_dwordx4 v[146:147], off
	v_lshl_add_u64 v[146:147], s[22:23], 0, v[134:135]
	s_add_i32 m0, s24, 0x2000
	s_nop 0
	global_load_lds_dwordx4 v[146:147], off
	s_waitcnt vmcnt(6)
	s_barrier
	s_setprio 1
	v_mfma_f32_16x16x32_bf16 v[52:55], v[204:207], v[166:169], v[52:55]
	v_mfma_f32_16x16x32_bf16 v[48:51], v[212:215], v[166:169], v[48:51]
	v_mfma_f32_16x16x32_bf16 v[36:39], v[204:207], v[180:183], v[36:39]
	v_mfma_f32_16x16x32_bf16 v[32:35], v[212:215], v[180:183], v[32:35]
	v_mfma_f32_16x16x32_bf16 v[20:23], v[204:207], v[188:191], v[20:23]
	v_mfma_f32_16x16x32_bf16 v[16:19], v[212:215], v[188:191], v[16:19]
	v_mfma_f32_16x16x32_bf16 v[4:7], v[204:207], v[196:199], v[4:7]
	v_mfma_f32_16x16x32_bf16 v[0:3], v[212:215], v[196:199], v[0:3]
	v_mfma_f32_16x16x32_bf16 v[52:55], v[208:211], v[170:173], v[52:55]
	v_mfma_f32_16x16x32_bf16 v[48:51], v[216:219], v[170:173], v[48:51]
	v_mfma_f32_16x16x32_bf16 v[36:39], v[208:211], v[184:187], v[36:39]
	v_mfma_f32_16x16x32_bf16 v[32:35], v[216:219], v[184:187], v[32:35]
	v_mfma_f32_16x16x32_bf16 v[20:23], v[208:211], v[192:195], v[20:23]
	v_mfma_f32_16x16x32_bf16 v[16:19], v[216:219], v[192:195], v[16:19]
	v_mfma_f32_16x16x32_bf16 v[4:7], v[208:211], v[200:203], v[4:7]
	v_mfma_f32_16x16x32_bf16 v[0:3], v[216:219], v[200:203], v[0:3]
	s_setprio 0
	s_add_i32 s45, s45, 2
	s_add_u32 s20, s20, 0x100
	s_addc_u32 s21, s21, 0
	s_add_u32 s43, s43, 0x100
	s_addc_u32 s44, s44, 0
	s_cmp_gt_u32 s45, 13
	s_barrier
	s_cbranch_scc0 .LBB0_1204
	s_mov_b64 s[24:25], 0x20000
	s_mov_b64 s[42:43], 0xa0000
	s_bfe_u32 vcc_lo, s18, 0x20003
	s_lshl_b32 vcc_lo, vcc_lo, 10
	s_add_i32 vcc_lo, vcc_lo, 0x20010
	v_lshl_add_u32 v236, v153, 2, vcc_lo
	ds_read_b32 v228, v236
	ds_read_b32 v229, v236 offset:64
	ds_read_b32 v230, v236 offset:128
	ds_read_b32 v231, v236 offset:192
	ds_read_b32 v232, v236 offset:512
	ds_read_b32 v233, v236 offset:576
	ds_read_b32 v234, v236 offset:640
	ds_read_b32 v235, v236 offset:704
	s_waitcnt lgkmcnt(0)
	v_lshl_add_u32 v148, s18, 8, v153
	v_ashrrev_i32_e32 v149, 31, v148
	v_lshl_or_b32 v166, s40, 8, v175
	v_ashrrev_i32_e32 v167, 31, v166
	v_lshlrev_b64 v[170:171], 13, v[148:149]
	v_lshlrev_b64 v[148:149], 1, v[166:167]
	v_lshl_add_u64 v[166:167], s[96:97], 0, v[170:171]
	v_lshl_add_u64 v[210:211], v[166:167], 0, v[148:149]
	s_mov_b32 s40, s10
	s_mov_b32 s18, s12
	s_mov_b64 s[22:23], s[16:17]
	s_mov_b64 s[20:21], s[14:15]
	v_mov_b32_e32 v182, v228
	v_pk_mul_f32 v[120:121], v[120:121], v[182:183] op_sel_hi:[1,0]
	v_pk_mul_f32 v[126:127], v[126:127], v[182:183] op_sel_hi:[1,0]
	v_pk_mul_f32 v[124:125], v[124:125], v[182:183] op_sel_hi:[1,0]
	v_pk_mul_f32 v[122:123], v[122:123], v[182:183] op_sel_hi:[1,0]
	v_max_f32_e32 v120, 0, v120
	v_max_f32_e32 v121, 0, v121
	v_max_f32_e32 v124, 0, v124
	v_max_f32_e32 v125, 0, v125
	v_pk_mul_f32 v[188:189], v[120:121], v[120:121]
	v_max_f32_e32 v120, 0, v126
	v_max_f32_e32 v122, 0, v122
	v_max_f32_e32 v121, 0, v127
	v_max_f32_e32 v123, 0, v123
	v_pk_mul_f32 v[124:125], v[124:125], v[124:125]
	v_pk_mul_f32 v[126:127], v[120:121], v[120:121]
	v_pk_mul_f32 v[192:193], v[122:123], v[122:123]
	v_pk_mul_f32 v[114:115], v[114:115], v[182:183] op_sel_hi:[1,0]
	v_cvt_pk_bf16_f32 v120, v124, v125
	v_cvt_pk_bf16_f32 v121, v126, v127
	v_cvt_pk_bf16_f32 v122, v188, v189
	v_cvt_pk_bf16_f32 v123, v192, v193
	v_pk_mul_f32 v[116:117], v[116:117], v[182:183] op_sel_hi:[1,0]
	v_pk_mul_f32 v[112:113], v[112:113], v[182:183] op_sel_hi:[1,0]
	v_max_f32_e32 v114, 0, v114
	v_max_f32_e32 v115, 0, v115
	global_store_dwordx4 v[210:211], v[120:123], off
	v_pk_mul_f32 v[118:119], v[118:119], v[182:183] op_sel_hi:[1,0]
	v_max_f32_e32 v116, 0, v116
	v_max_f32_e32 v112, 0, v112
	v_max_f32_e32 v117, 0, v117
	v_max_f32_e32 v113, 0, v113
	v_pk_mul_f32 v[122:123], v[114:115], v[114:115]
	v_pk_mul_f32 v[116:117], v[116:117], v[116:117]
	v_pk_mul_f32 v[120:121], v[112:113], v[112:113]
	v_max_f32_e32 v112, 0, v118
	v_max_f32_e32 v113, 0, v119
	v_pk_mul_f32 v[118:119], v[112:113], v[112:113]
	v_cvt_pk_bf16_f32 v112, v116, v117
	v_cvt_pk_bf16_f32 v113, v118, v119
	v_cvt_pk_bf16_f32 v114, v120, v121
	v_cvt_pk_bf16_f32 v115, v122, v123
	global_store_dwordx4 v[210:211], v[112:115], off offset:256
	s_nop 1
	v_mov_b32_e32 v112, v229
	v_pk_mul_f32 v[104:105], v[104:105], v[112:113] op_sel_hi:[1,0]
; __device__ __forceinline__ unsigned pk2(float lo, float hi) { const f32x2 v = (f32x2){lo, hi}; const bf16x2_t b = __builtin_convertvector(v, bf16x2_t); return __builtin_bit_cast(unsigned, b); }
;     __device__ __forceinline__ void operator()(const f32x4 (&acc)[2][2][4][2], const Unit& u, int wr, int wc, int fr, int fq, const float (&)[8]) const {
;     ...
;             for (int m = 0; m < 4; ++m) { const int row = row0 + ai * HALF + m * 16; const float rs = rsqrtf(ep[ai * 4 + m] * (1.0f / 1024.0f) + EPS);
;                 u16* rowp = O + (size_t)row * ldc + col0;
; #pragma unroll
;                 for (int bj = 0; bj < 2; ++bj) { f32x4 v0 = acc[ai][bj][m][0] * rs, v1 = acc[ai][bj][m][1] * rs;
;                     if (ACT == 1) {
; #pragma unroll
;                         for (int j = 0; j < 4; ++j) { const float a0 = fmaxf(v0[j], 0.f), a1 = fmaxf(v1[j], 0.f); v0[j] = a0 * a0; v1[j] = a1 * a1; } }
;                     u32x4 w; w.x = pk2(v0[0], v0[1]); w.y = pk2(v0[2], v0[3]); w.z = pk2(v1[0], v1[1]); w.w = pk2(v1[2], v1[3]);
;                     *(u32x4*)(rowp + bj * HALF) = w; } }
	v_pk_mul_f32 v[110:111], v[110:111], v[112:113] op_sel_hi:[1,0]
	v_pk_mul_f32 v[108:109], v[108:109], v[112:113] op_sel_hi:[1,0]
	v_pk_mul_f32 v[106:107], v[106:107], v[112:113] op_sel_hi:[1,0]
	v_max_f32_e32 v104, 0, v104
	v_max_f32_e32 v105, 0, v105
	v_max_f32_e32 v108, 0, v108
	v_max_f32_e32 v109, 0, v109
	v_pk_mul_f32 v[116:117], v[104:105], v[104:105]
	v_max_f32_e32 v104, 0, v110
	v_max_f32_e32 v106, 0, v106
	v_max_f32_e32 v105, 0, v111
	v_max_f32_e32 v107, 0, v107
	v_pk_mul_f32 v[108:109], v[108:109], v[108:109]
	v_pk_mul_f32 v[110:111], v[104:105], v[104:105]
	v_pk_mul_f32 v[118:119], v[106:107], v[106:107]
	v_pk_mul_f32 v[96:97], v[96:97], v[112:113] op_sel_hi:[1,0]
	v_lshl_add_u64 v[114:115], v[210:211], 0, s[24:25]
	v_cvt_pk_bf16_f32 v104, v108, v109
	v_cvt_pk_bf16_f32 v105, v110, v111
	v_cvt_pk_bf16_f32 v106, v116, v117
	v_cvt_pk_bf16_f32 v107, v118, v119
	v_pk_mul_f32 v[102:103], v[102:103], v[112:113] op_sel_hi:[1,0]
	v_max_f32_e32 v96, 0, v96
	v_max_f32_e32 v97, 0, v97
	global_store_dwordx4 v[114:115], v[104:107], off
	v_pk_mul_f32 v[100:101], v[100:101], v[112:113] op_sel_hi:[1,0]
	v_pk_mul_f32 v[98:99], v[98:99], v[112:113] op_sel_hi:[1,0]
	v_pk_mul_f32 v[104:105], v[96:97], v[96:97]
	v_max_f32_e32 v96, 0, v102
	v_max_f32_e32 v97, 0, v103
	v_max_f32_e32 v100, 0, v100
	v_max_f32_e32 v101, 0, v101
	v_pk_mul_f32 v[100:101], v[100:101], v[100:101]
	v_pk_mul_f32 v[108:109], v[96:97], v[96:97]
	v_cvt_pk_bf16_f32 v96, v100, v101
	v_max_f32_e32 v98, 0, v98
	v_max_f32_e32 v99, 0, v99
	v_pk_mul_f32 v[110:111], v[98:99], v[98:99]
	v_cvt_pk_bf16_f32 v97, v108, v109
	v_cvt_pk_bf16_f32 v98, v104, v105
	v_cvt_pk_bf16_f32 v99, v110, v111
	global_store_dwordx4 v[114:115], v[96:99], off offset:256
	s_nop 1
	v_lshl_add_u64 v[98:99], v[114:115], 0, s[24:25]
	v_mov_b32_e32 v100, v230
	v_pk_mul_f32 v[88:89], v[88:89], v[100:101] op_sel_hi:[1,0]
	v_pk_mul_f32 v[94:95], v[94:95], v[100:101] op_sel_hi:[1,0]
	v_pk_mul_f32 v[92:93], v[92:93], v[100:101] op_sel_hi:[1,0]
	v_pk_mul_f32 v[90:91], v[90:91], v[100:101] op_sel_hi:[1,0]
	v_max_f32_e32 v88, 0, v88
	v_max_f32_e32 v89, 0, v89
	v_max_f32_e32 v92, 0, v92
	v_max_f32_e32 v93, 0, v93
	v_pk_mul_f32 v[102:103], v[88:89], v[88:89]
	v_max_f32_e32 v88, 0, v94
	v_max_f32_e32 v90, 0, v90
	v_max_f32_e32 v89, 0, v95
	v_max_f32_e32 v91, 0, v91
	v_pk_mul_f32 v[92:93], v[92:93], v[92:93]
	v_pk_mul_f32 v[94:95], v[88:89], v[88:89]
	v_pk_mul_f32 v[104:105], v[90:91], v[90:91]
	v_pk_mul_f32 v[82:83], v[82:83], v[100:101] op_sel_hi:[1,0]
	v_cvt_pk_bf16_f32 v88, v92, v93
	v_cvt_pk_bf16_f32 v89, v94, v95
	v_cvt_pk_bf16_f32 v90, v102, v103
	v_cvt_pk_bf16_f32 v91, v104, v105
	v_pk_mul_f32 v[84:85], v[84:85], v[100:101] op_sel_hi:[1,0]
	v_pk_mul_f32 v[80:81], v[80:81], v[100:101] op_sel_hi:[1,0]
	v_max_f32_e32 v82, 0, v82
	v_max_f32_e32 v83, 0, v83
	global_store_dwordx4 v[98:99], v[88:91], off
	v_pk_mul_f32 v[86:87], v[86:87], v[100:101] op_sel_hi:[1,0]
	v_max_f32_e32 v84, 0, v84
	v_max_f32_e32 v80, 0, v80
	v_max_f32_e32 v85, 0, v85
	v_max_f32_e32 v81, 0, v81
	v_pk_mul_f32 v[90:91], v[82:83], v[82:83]
	v_pk_mul_f32 v[84:85], v[84:85], v[84:85]
	v_pk_mul_f32 v[88:89], v[80:81], v[80:81]
	v_max_f32_e32 v80, 0, v86
	v_max_f32_e32 v81, 0, v87
	v_pk_mul_f32 v[86:87], v[80:81], v[80:81]
	v_cvt_pk_bf16_f32 v80, v84, v85
	v_cvt_pk_bf16_f32 v81, v86, v87
	v_cvt_pk_bf16_f32 v82, v88, v89
	v_cvt_pk_bf16_f32 v83, v90, v91
	global_store_dwordx4 v[98:99], v[80:83], off offset:256
	s_nop 1
	v_mov_b32_e32 v80, v231
	v_pk_mul_f32 v[72:73], v[72:73], v[80:81] op_sel_hi:[1,0]
	v_pk_mul_f32 v[78:79], v[78:79], v[80:81] op_sel_hi:[1,0]
	v_pk_mul_f32 v[76:77], v[76:77], v[80:81] op_sel_hi:[1,0]
	v_pk_mul_f32 v[74:75], v[74:75], v[80:81] op_sel_hi:[1,0]
	v_max_f32_e32 v72, 0, v72
	v_max_f32_e32 v73, 0, v73
	v_max_f32_e32 v76, 0, v76
	v_max_f32_e32 v77, 0, v77
	v_pk_mul_f32 v[84:85], v[72:73], v[72:73]
	v_max_f32_e32 v72, 0, v78
	v_max_f32_e32 v74, 0, v74
	v_max_f32_e32 v73, 0, v79
	v_max_f32_e32 v75, 0, v75
	v_pk_mul_f32 v[76:77], v[76:77], v[76:77]
	v_pk_mul_f32 v[78:79], v[72:73], v[72:73]
	v_pk_mul_f32 v[86:87], v[74:75], v[74:75]
	v_pk_mul_f32 v[64:65], v[64:65], v[80:81] op_sel_hi:[1,0]
	v_lshl_add_u64 v[82:83], v[98:99], 0, s[24:25]
	v_cvt_pk_bf16_f32 v72, v76, v77
	v_cvt_pk_bf16_f32 v73, v78, v79
	v_cvt_pk_bf16_f32 v74, v84, v85
	v_cvt_pk_bf16_f32 v75, v86, v87
	v_pk_mul_f32 v[70:71], v[70:71], v[80:81] op_sel_hi:[1,0]
	v_max_f32_e32 v64, 0, v64
	v_max_f32_e32 v65, 0, v65
	global_store_dwordx4 v[82:83], v[72:75], off
	v_pk_mul_f32 v[68:69], v[68:69], v[80:81] op_sel_hi:[1,0]
	v_pk_mul_f32 v[66:67], v[66:67], v[80:81] op_sel_hi:[1,0]
	v_pk_mul_f32 v[72:73], v[64:65], v[64:65]
	v_max_f32_e32 v64, 0, v70
	v_max_f32_e32 v65, 0, v71
	v_max_f32_e32 v68, 0, v68
	v_max_f32_e32 v69, 0, v69
	v_pk_mul_f32 v[68:69], v[68:69], v[68:69]
	v_pk_mul_f32 v[76:77], v[64:65], v[64:65]
	v_cvt_pk_bf16_f32 v64, v68, v69
	v_max_f32_e32 v66, 0, v66
	v_max_f32_e32 v67, 0, v67
	v_pk_mul_f32 v[78:79], v[66:67], v[66:67]
	v_cvt_pk_bf16_f32 v65, v76, v77
	v_cvt_pk_bf16_f32 v66, v72, v73
	v_cvt_pk_bf16_f32 v67, v78, v79
	global_store_dwordx4 v[82:83], v[64:67], off offset:256
	s_nop 1
	v_lshl_add_u64 v[66:67], v[82:83], 0, s[42:43]
	v_mov_b32_e32 v68, v232
	v_pk_mul_f32 v[56:57], v[56:57], v[68:69] op_sel_hi:[1,0]
	v_pk_mul_f32 v[62:63], v[62:63], v[68:69] op_sel_hi:[1,0]
	v_pk_mul_f32 v[60:61], v[60:61], v[68:69] op_sel_hi:[1,0]
	v_pk_mul_f32 v[58:59], v[58:59], v[68:69] op_sel_hi:[1,0]
	v_max_f32_e32 v56, 0, v56
	v_max_f32_e32 v57, 0, v57
	v_max_f32_e32 v60, 0, v60
	v_max_f32_e32 v61, 0, v61
	v_pk_mul_f32 v[70:71], v[56:57], v[56:57]
	v_max_f32_e32 v56, 0, v62
; __device__ __forceinline__ unsigned pk2(float lo, float hi) { const f32x2 v = (f32x2){lo, hi}; const bf16x2_t b = __builtin_convertvector(v, bf16x2_t); return __builtin_bit_cast(unsigned, b); }
;     __device__ __forceinline__ void operator()(const f32x4 (&acc)[2][2][4][2], const Unit& u, int wr, int wc, int fr, int fq, const float (&)[8]) const {
;     ...
;             for (int m = 0; m < 4; ++m) { const int row = row0 + ai * HALF + m * 16; const float rs = rsqrtf(ep[ai * 4 + m] * (1.0f / 1024.0f) + EPS);
;                 u16* rowp = O + (size_t)row * ldc + col0;
; #pragma unroll
;                 for (int bj = 0; bj < 2; ++bj) { f32x4 v0 = acc[ai][bj][m][0] * rs, v1 = acc[ai][bj][m][1] * rs;
;                     if (ACT == 1) {
; #pragma unroll
;                         for (int j = 0; j < 4; ++j) { const float a0 = fmaxf(v0[j], 0.f), a1 = fmaxf(v1[j], 0.f); v0[j] = a0 * a0; v1[j] = a1 * a1; } }
;                     u32x4 w; w.x = pk2(v0[0], v0[1]); w.y = pk2(v0[2], v0[3]); w.z = pk2(v1[0], v1[1]); w.w = pk2(v1[2], v1[3]);
;                     *(u32x4*)(rowp + bj * HALF) = w; } }
; template <class Epi>
; __device__ __forceinline__ void gemm_phase(LAS unsigned char* lds, const Gemm g, const StaticOrder& S, const Epi& E) {
;     ...
;         E(acc, cur, wr, wc, fr, fq, epre);
;         if (!has_next) break;
	v_max_f32_e32 v58, 0, v58
	v_max_f32_e32 v57, 0, v63
	v_max_f32_e32 v59, 0, v59
	v_pk_mul_f32 v[60:61], v[60:61], v[60:61]
	v_pk_mul_f32 v[62:63], v[56:57], v[56:57]
	v_pk_mul_f32 v[72:73], v[58:59], v[58:59]
	v_pk_mul_f32 v[50:51], v[50:51], v[68:69] op_sel_hi:[1,0]
	v_cvt_pk_bf16_f32 v56, v60, v61
	v_cvt_pk_bf16_f32 v57, v62, v63
	v_cvt_pk_bf16_f32 v58, v70, v71
	v_cvt_pk_bf16_f32 v59, v72, v73
	v_pk_mul_f32 v[52:53], v[52:53], v[68:69] op_sel_hi:[1,0]
	v_pk_mul_f32 v[48:49], v[48:49], v[68:69] op_sel_hi:[1,0]
	v_max_f32_e32 v50, 0, v50
	v_max_f32_e32 v51, 0, v51
	global_store_dwordx4 v[66:67], v[56:59], off
	v_pk_mul_f32 v[54:55], v[54:55], v[68:69] op_sel_hi:[1,0]
	v_max_f32_e32 v52, 0, v52
	v_max_f32_e32 v48, 0, v48
	v_max_f32_e32 v53, 0, v53
	v_max_f32_e32 v49, 0, v49
	v_pk_mul_f32 v[58:59], v[50:51], v[50:51]
	v_pk_mul_f32 v[52:53], v[52:53], v[52:53]
	v_pk_mul_f32 v[56:57], v[48:49], v[48:49]
	v_max_f32_e32 v48, 0, v54
	v_max_f32_e32 v49, 0, v55
	v_pk_mul_f32 v[54:55], v[48:49], v[48:49]
	v_cvt_pk_bf16_f32 v48, v52, v53
	v_cvt_pk_bf16_f32 v49, v54, v55
	v_cvt_pk_bf16_f32 v50, v56, v57
	v_cvt_pk_bf16_f32 v51, v58, v59
	global_store_dwordx4 v[66:67], v[48:51], off offset:256
	s_nop 1
	v_mov_b32_e32 v48, v233
	v_pk_mul_f32 v[40:41], v[40:41], v[48:49] op_sel_hi:[1,0]
	v_pk_mul_f32 v[46:47], v[46:47], v[48:49] op_sel_hi:[1,0]
	v_pk_mul_f32 v[44:45], v[44:45], v[48:49] op_sel_hi:[1,0]
	v_pk_mul_f32 v[42:43], v[42:43], v[48:49] op_sel_hi:[1,0]
	v_max_f32_e32 v40, 0, v40
	v_max_f32_e32 v41, 0, v41
	v_max_f32_e32 v44, 0, v44
	v_max_f32_e32 v45, 0, v45
	v_pk_mul_f32 v[52:53], v[40:41], v[40:41]
	v_max_f32_e32 v40, 0, v46
	v_max_f32_e32 v42, 0, v42
	v_max_f32_e32 v41, 0, v47
	v_max_f32_e32 v43, 0, v43
	v_pk_mul_f32 v[44:45], v[44:45], v[44:45]
	v_pk_mul_f32 v[46:47], v[40:41], v[40:41]
	v_pk_mul_f32 v[54:55], v[42:43], v[42:43]
	v_pk_mul_f32 v[32:33], v[32:33], v[48:49] op_sel_hi:[1,0]
	v_lshl_add_u64 v[50:51], v[66:67], 0, s[24:25]
	v_cvt_pk_bf16_f32 v40, v44, v45
	v_cvt_pk_bf16_f32 v41, v46, v47
	v_cvt_pk_bf16_f32 v42, v52, v53
	v_cvt_pk_bf16_f32 v43, v54, v55
	v_pk_mul_f32 v[38:39], v[38:39], v[48:49] op_sel_hi:[1,0]
	v_max_f32_e32 v32, 0, v32
	v_max_f32_e32 v33, 0, v33
	global_store_dwordx4 v[50:51], v[40:43], off
	v_pk_mul_f32 v[36:37], v[36:37], v[48:49] op_sel_hi:[1,0]
	v_pk_mul_f32 v[34:35], v[34:35], v[48:49] op_sel_hi:[1,0]
	v_pk_mul_f32 v[40:41], v[32:33], v[32:33]
	v_max_f32_e32 v32, 0, v38
	v_max_f32_e32 v33, 0, v39
	v_max_f32_e32 v36, 0, v36
	v_max_f32_e32 v37, 0, v37
	v_pk_mul_f32 v[36:37], v[36:37], v[36:37]
	v_pk_mul_f32 v[44:45], v[32:33], v[32:33]
	v_cvt_pk_bf16_f32 v32, v36, v37
	v_max_f32_e32 v34, 0, v34
	v_max_f32_e32 v35, 0, v35
	v_pk_mul_f32 v[46:47], v[34:35], v[34:35]
	v_cvt_pk_bf16_f32 v33, v44, v45
	v_cvt_pk_bf16_f32 v34, v40, v41
	v_cvt_pk_bf16_f32 v35, v46, v47
	global_store_dwordx4 v[50:51], v[32:35], off offset:256
	s_nop 1
	v_lshl_add_u64 v[34:35], v[50:51], 0, s[24:25]
	v_mov_b32_e32 v36, v234
	v_pk_mul_f32 v[24:25], v[24:25], v[36:37] op_sel_hi:[1,0]
	v_pk_mul_f32 v[30:31], v[30:31], v[36:37] op_sel_hi:[1,0]
	v_pk_mul_f32 v[28:29], v[28:29], v[36:37] op_sel_hi:[1,0]
	v_pk_mul_f32 v[26:27], v[26:27], v[36:37] op_sel_hi:[1,0]
	v_max_f32_e32 v24, 0, v24
	v_max_f32_e32 v25, 0, v25
	v_max_f32_e32 v28, 0, v28
	v_max_f32_e32 v29, 0, v29
	v_pk_mul_f32 v[38:39], v[24:25], v[24:25]
	v_max_f32_e32 v24, 0, v30
	v_max_f32_e32 v26, 0, v26
	v_max_f32_e32 v25, 0, v31
	v_max_f32_e32 v27, 0, v27
	v_pk_mul_f32 v[28:29], v[28:29], v[28:29]
	v_pk_mul_f32 v[30:31], v[24:25], v[24:25]
	v_pk_mul_f32 v[40:41], v[26:27], v[26:27]
	v_pk_mul_f32 v[18:19], v[18:19], v[36:37] op_sel_hi:[1,0]
	v_cvt_pk_bf16_f32 v24, v28, v29
	v_cvt_pk_bf16_f32 v25, v30, v31
	v_cvt_pk_bf16_f32 v26, v38, v39
	v_cvt_pk_bf16_f32 v27, v40, v41
	v_pk_mul_f32 v[20:21], v[20:21], v[36:37] op_sel_hi:[1,0]
	v_pk_mul_f32 v[16:17], v[16:17], v[36:37] op_sel_hi:[1,0]
	v_max_f32_e32 v18, 0, v18
	v_max_f32_e32 v19, 0, v19
	global_store_dwordx4 v[34:35], v[24:27], off
	v_pk_mul_f32 v[22:23], v[22:23], v[36:37] op_sel_hi:[1,0]
	v_max_f32_e32 v20, 0, v20
	v_max_f32_e32 v16, 0, v16
	v_max_f32_e32 v21, 0, v21
	v_max_f32_e32 v17, 0, v17
	v_pk_mul_f32 v[26:27], v[18:19], v[18:19]
	v_pk_mul_f32 v[20:21], v[20:21], v[20:21]
	v_pk_mul_f32 v[24:25], v[16:17], v[16:17]
	v_max_f32_e32 v16, 0, v22
	v_max_f32_e32 v17, 0, v23
	v_pk_mul_f32 v[22:23], v[16:17], v[16:17]
	v_cvt_pk_bf16_f32 v16, v20, v21
	v_cvt_pk_bf16_f32 v17, v22, v23
	v_cvt_pk_bf16_f32 v18, v24, v25
	v_cvt_pk_bf16_f32 v19, v26, v27
	global_store_dwordx4 v[34:35], v[16:19], off offset:256
	s_nop 1
	v_mov_b32_e32 v16, v235
	v_pk_mul_f32 v[8:9], v[8:9], v[16:17] op_sel_hi:[1,0]
	v_pk_mul_f32 v[14:15], v[14:15], v[16:17] op_sel_hi:[1,0]
	v_pk_mul_f32 v[12:13], v[12:13], v[16:17] op_sel_hi:[1,0]
	v_pk_mul_f32 v[10:11], v[10:11], v[16:17] op_sel_hi:[1,0]
	v_max_f32_e32 v8, 0, v8
	v_max_f32_e32 v9, 0, v9
	v_max_f32_e32 v12, 0, v12
	v_max_f32_e32 v13, 0, v13
	v_pk_mul_f32 v[20:21], v[8:9], v[8:9]
	v_max_f32_e32 v8, 0, v14
	v_max_f32_e32 v10, 0, v10
	v_max_f32_e32 v9, 0, v15
	v_max_f32_e32 v11, 0, v11
	v_pk_mul_f32 v[12:13], v[12:13], v[12:13]
	v_pk_mul_f32 v[14:15], v[8:9], v[8:9]
	v_pk_mul_f32 v[22:23], v[10:11], v[10:11]
	v_pk_mul_f32 v[0:1], v[0:1], v[16:17] op_sel_hi:[1,0]
	v_lshl_add_u64 v[18:19], v[34:35], 0, s[24:25]
	v_cvt_pk_bf16_f32 v8, v12, v13
	v_cvt_pk_bf16_f32 v9, v14, v15
	v_cvt_pk_bf16_f32 v10, v20, v21
	v_cvt_pk_bf16_f32 v11, v22, v23
	v_pk_mul_f32 v[6:7], v[6:7], v[16:17] op_sel_hi:[1,0]
	v_pk_mul_f32 v[4:5], v[4:5], v[16:17] op_sel_hi:[1,0]
	v_pk_mul_f32 v[2:3], v[2:3], v[16:17] op_sel_hi:[1,0]
	v_max_f32_e32 v0, 0, v0
	v_max_f32_e32 v1, 0, v1
	global_store_dwordx4 v[18:19], v[8:11], off
	v_max_f32_e32 v4, 0, v4
	v_max_f32_e32 v5, 0, v5
	v_pk_mul_f32 v[8:9], v[0:1], v[0:1]
	v_max_f32_e32 v0, 0, v6
	v_max_f32_e32 v2, 0, v2
	v_max_f32_e32 v1, 0, v7
	v_max_f32_e32 v3, 0, v3
	v_pk_mul_f32 v[4:5], v[4:5], v[4:5]
	v_pk_mul_f32 v[6:7], v[0:1], v[0:1]
	v_pk_mul_f32 v[10:11], v[2:3], v[2:3]
	v_cvt_pk_bf16_f32 v0, v4, v5
	v_cvt_pk_bf16_f32 v1, v6, v7
	v_cvt_pk_bf16_f32 v2, v8, v9
	v_cvt_pk_bf16_f32 v3, v10, v11
	s_and_b64 vcc, exec, s[0:1]
	global_store_dwordx4 v[18:19], v[0:3], off offset:256
	s_cbranch_vccz .LBB0_1197
	s_waitcnt vmcnt(0)
	s_cmpk_gt_u32 s7, 0xff
	s_cbranch_scc1 .LBB0_1208
	s_barrier
